# GEMM epilogue butterflies (lane^16, lane^32 sums for qk-norm and row sum-of-squares) use v_permlane16/32_swap instead of ds_bpermute
# speedup vs baseline: 1.0292x; 1.0042x over previous
.LBB0_209:
	v_pk_mul_f32 v[180:181], v[144:145], v[144:145]
	v_pk_mul_f32 v[188:189], v[142:143], v[142:143]
	v_mul_f32_e32 v0, v134, v134
	v_pk_mov_b32 v[190:191], v[188:189], v[180:181] op_sel:[1,0]
	v_mov_b32_e32 v189, v181
	v_pk_add_f32 v[180:181], v[190:191], v[188:189]
	v_pk_mul_f32 v[188:189], v[140:141], v[140:141]
	v_pk_mul_f32 v[190:191], v[138:139], v[138:139]
	v_pk_add_f32 v[180:181], v[180:181], v[180:181] op_sel_hi:[0,1]
	v_pk_mov_b32 v[192:193], v[190:191], v[188:189] op_sel:[1,0]
	v_mov_b32_e32 v191, v189
	v_pk_add_f32 v[188:189], v[192:193], v[190:191]
	v_pk_fma_f32 v[190:191], v[134:135], v[134:135], v[0:1] op_sel_hi:[1,1,0]
	v_mul_f32_e32 v0, v136, v136
	v_pk_add_f32 v[188:189], v[188:189], v[188:189] op_sel_hi:[0,1]
	v_pk_fma_f32 v[192:193], v[136:137], v[136:137], v[0:1] op_sel_hi:[1,1,0]
	v_mul_f32_e32 v190, v130, v130
	v_mul_f32_e32 v192, v131, v131
	v_mul_f32_e32 v188, v132, v132
	v_mul_f32_e32 v180, v133, v133
	v_pk_add_f32 v[190:191], v[190:191], v[192:193]
	v_pk_add_f32 v[180:181], v[188:189], v[180:181]
	v_xor_b32_e32 v179, 16, v215
	v_pk_add_f32 v[180:181], v[190:191], v[180:181]
	s_nop 0
	v_add_f32_e32 v0, v180, v181
	v_and_b32_e32 v180, 64, v215
	v_add_u32_e32 v180, 64, v180
	v_cmp_lt_i32_e32 vcc, v179, v180
	s_nop 1
	v_cndmask_b32_e32 v179, v215, v179, vcc
	v_lshlrev_b32_e32 v179, 2, v179
	v_mov_b32_e32 v179, v0
	s_nop 1
	v_permlane16_swap_b32_e32 v179, v0
	s_waitcnt lgkmcnt(0)
	v_add_f32_e32 v0, v0, v179
	v_xor_b32_e32 v179, 32, v215
	v_cmp_lt_i32_e32 vcc, v179, v180
	s_nop 1
	v_cndmask_b32_e32 v179, v215, v179, vcc
	v_lshlrev_b32_e32 v179, 2, v179
	v_mov_b32_e32 v179, v0
	s_nop 1
	v_permlane32_swap_b32_e32 v179, v0
	s_waitcnt lgkmcnt(0)
	v_add_f32_e32 v0, v0, v179
	v_mul_f32_e32 v0, v174, v0
	v_mul_f32_e32 v0, v174, v0
	v_max_f32_e32 v187, 0, v0
	s_mov_b64 s[12:13], -1
	s_and_b64 vcc, exec, s[86:87]
	s_cbranch_vccz .LBB0_211

.LBB0_224:
	v_pk_mul_f32 v[134:135], v[128:129], v[128:129]
	v_pk_mul_f32 v[136:137], v[126:127], v[126:127]
	v_mul_f32_e32 v0, v118, v118
	v_pk_mov_b32 v[138:139], v[136:137], v[134:135] op_sel:[1,0]
	v_mov_b32_e32 v137, v135
	v_pk_add_f32 v[134:135], v[138:139], v[136:137]
	v_pk_mul_f32 v[136:137], v[124:125], v[124:125]
	v_pk_mul_f32 v[138:139], v[122:123], v[122:123]
	v_pk_add_f32 v[134:135], v[134:135], v[134:135] op_sel_hi:[0,1]
	v_pk_mov_b32 v[140:141], v[138:139], v[136:137] op_sel:[1,0]
	v_mov_b32_e32 v139, v137
	v_pk_add_f32 v[136:137], v[140:141], v[138:139]
	v_pk_fma_f32 v[138:139], v[118:119], v[118:119], v[0:1] op_sel_hi:[1,1,0]
	v_mul_f32_e32 v0, v120, v120
	v_pk_add_f32 v[136:137], v[136:137], v[136:137] op_sel_hi:[0,1]
	v_pk_fma_f32 v[140:141], v[120:121], v[120:121], v[0:1] op_sel_hi:[1,1,0]
	v_mul_f32_e32 v138, v114, v114
	v_mul_f32_e32 v140, v115, v115
	v_mul_f32_e32 v136, v116, v116
	v_mul_f32_e32 v134, v117, v117
	v_pk_add_f32 v[138:139], v[138:139], v[140:141]
	v_pk_add_f32 v[134:135], v[136:137], v[134:135]
	v_xor_b32_e32 v133, 16, v215
	v_pk_add_f32 v[134:135], v[138:139], v[134:135]
	s_nop 0
	v_add_f32_e32 v0, v134, v135
	v_and_b32_e32 v134, 64, v215
	v_add_u32_e32 v134, 64, v134
	v_cmp_lt_i32_e32 vcc, v133, v134
	s_nop 1
	v_cndmask_b32_e32 v133, v215, v133, vcc
	v_lshlrev_b32_e32 v133, 2, v133
	v_mov_b32_e32 v133, v0
	s_nop 1
	v_permlane16_swap_b32_e32 v133, v0
	s_waitcnt lgkmcnt(0)
	v_add_f32_e32 v0, v0, v133
	v_xor_b32_e32 v133, 32, v215
	v_cmp_lt_i32_e32 vcc, v133, v134
	s_nop 1
	v_cndmask_b32_e32 v133, v215, v133, vcc
	v_lshlrev_b32_e32 v133, 2, v133
	v_mov_b32_e32 v133, v0
	s_nop 1
	v_permlane32_swap_b32_e32 v133, v0
	s_waitcnt lgkmcnt(0)
	v_add_f32_e32 v0, v0, v133
	v_mul_f32_e32 v0, v174, v0
	v_mul_f32_e32 v0, v174, v0
	v_max_f32_e32 v133, v187, v187
	v_max_f32_e32 v187, v133, v0

.LBB0_241:
	v_pk_mul_f32 v[118:119], v[112:113], v[112:113]
	v_pk_mul_f32 v[120:121], v[110:111], v[110:111]
	v_mul_f32_e32 v0, v102, v102
	v_pk_mov_b32 v[122:123], v[120:121], v[118:119] op_sel:[1,0]
	v_mov_b32_e32 v121, v119
	v_pk_add_f32 v[118:119], v[122:123], v[120:121]
	v_pk_mul_f32 v[120:121], v[108:109], v[108:109]
	v_pk_mul_f32 v[122:123], v[106:107], v[106:107]
	v_pk_add_f32 v[118:119], v[118:119], v[118:119] op_sel_hi:[0,1]
	v_pk_mov_b32 v[124:125], v[122:123], v[120:121] op_sel:[1,0]
	v_mov_b32_e32 v123, v121
	v_pk_add_f32 v[120:121], v[124:125], v[122:123]
	v_pk_fma_f32 v[122:123], v[102:103], v[102:103], v[0:1] op_sel_hi:[1,1,0]
	v_mul_f32_e32 v0, v104, v104
	v_pk_add_f32 v[120:121], v[120:121], v[120:121] op_sel_hi:[0,1]
	v_pk_fma_f32 v[124:125], v[104:105], v[104:105], v[0:1] op_sel_hi:[1,1,0]
	v_mul_f32_e32 v122, v98, v98
	v_mul_f32_e32 v124, v99, v99
	v_mul_f32_e32 v120, v100, v100
	v_mul_f32_e32 v118, v101, v101
	v_pk_add_f32 v[122:123], v[122:123], v[124:125]
	v_pk_add_f32 v[118:119], v[120:121], v[118:119]
	v_xor_b32_e32 v117, 16, v215
	v_pk_add_f32 v[118:119], v[122:123], v[118:119]
	s_nop 0
	v_add_f32_e32 v0, v118, v119
	v_and_b32_e32 v118, 64, v215
	v_add_u32_e32 v118, 64, v118
	v_cmp_lt_i32_e32 vcc, v117, v118
	s_nop 1
	v_cndmask_b32_e32 v117, v215, v117, vcc
	v_lshlrev_b32_e32 v117, 2, v117
	v_mov_b32_e32 v117, v0
	s_nop 1
	v_permlane16_swap_b32_e32 v117, v0
	s_waitcnt lgkmcnt(0)
	v_add_f32_e32 v0, v0, v117
	v_xor_b32_e32 v117, 32, v215
	v_cmp_lt_i32_e32 vcc, v117, v118
	s_nop 1
	v_cndmask_b32_e32 v117, v215, v117, vcc
	v_lshlrev_b32_e32 v117, 2, v117
	v_mov_b32_e32 v117, v0
	s_nop 1
	v_permlane32_swap_b32_e32 v117, v0
	s_waitcnt lgkmcnt(0)
	v_add_f32_e32 v0, v0, v117
	v_mul_f32_e32 v0, v174, v0
	v_mul_f32_e32 v0, v174, v0
	v_max_f32_e32 v117, v187, v187
	v_max_f32_e32 v187, v117, v0

.LBB0_257:
	v_pk_mul_f32 v[102:103], v[96:97], v[96:97]
	v_pk_mul_f32 v[104:105], v[94:95], v[94:95]
	v_mul_f32_e32 v0, v86, v86
	v_pk_mov_b32 v[106:107], v[104:105], v[102:103] op_sel:[1,0]
	v_mov_b32_e32 v105, v103
	v_pk_add_f32 v[102:103], v[106:107], v[104:105]
	v_pk_mul_f32 v[104:105], v[92:93], v[92:93]
	v_pk_mul_f32 v[106:107], v[90:91], v[90:91]
	v_pk_add_f32 v[102:103], v[102:103], v[102:103] op_sel_hi:[0,1]
	v_pk_mov_b32 v[108:109], v[106:107], v[104:105] op_sel:[1,0]
	v_mov_b32_e32 v107, v105
	v_pk_add_f32 v[104:105], v[108:109], v[106:107]
	v_pk_fma_f32 v[106:107], v[86:87], v[86:87], v[0:1] op_sel_hi:[1,1,0]
	v_mul_f32_e32 v0, v88, v88
	v_pk_add_f32 v[104:105], v[104:105], v[104:105] op_sel_hi:[0,1]
	v_pk_fma_f32 v[108:109], v[88:89], v[88:89], v[0:1] op_sel_hi:[1,1,0]
	v_mul_f32_e32 v106, v82, v82
	v_mul_f32_e32 v108, v83, v83
	v_mul_f32_e32 v104, v84, v84
	v_mul_f32_e32 v102, v85, v85
	v_pk_add_f32 v[106:107], v[106:107], v[108:109]
	v_pk_add_f32 v[102:103], v[104:105], v[102:103]
	v_xor_b32_e32 v101, 16, v215
	v_pk_add_f32 v[102:103], v[106:107], v[102:103]
	s_nop 0
	v_add_f32_e32 v0, v102, v103
	v_and_b32_e32 v102, 64, v215
	v_add_u32_e32 v102, 64, v102
	v_cmp_lt_i32_e32 vcc, v101, v102
	s_nop 1
	v_cndmask_b32_e32 v101, v215, v101, vcc
	v_lshlrev_b32_e32 v101, 2, v101
	v_mov_b32_e32 v101, v0
	s_nop 1
	v_permlane16_swap_b32_e32 v101, v0
	s_waitcnt lgkmcnt(0)
	v_add_f32_e32 v0, v0, v101
	v_xor_b32_e32 v101, 32, v215
	v_cmp_lt_i32_e32 vcc, v101, v102
	s_nop 1
	v_cndmask_b32_e32 v101, v215, v101, vcc
	v_lshlrev_b32_e32 v101, 2, v101
	v_mov_b32_e32 v101, v0
	s_nop 1
	v_permlane32_swap_b32_e32 v101, v0
	s_waitcnt lgkmcnt(0)
	v_add_f32_e32 v0, v0, v101
	v_mul_f32_e32 v0, v174, v0
	v_mul_f32_e32 v0, v174, v0
	v_max_f32_e32 v101, v187, v187
	v_max_f32_e32 v187, v101, v0

.LBB0_273:
	v_pk_mul_f32 v[86:87], v[80:81], v[80:81]
	v_pk_mul_f32 v[88:89], v[78:79], v[78:79]
	v_mul_f32_e32 v0, v70, v70
	v_pk_mov_b32 v[90:91], v[88:89], v[86:87] op_sel:[1,0]
	v_mov_b32_e32 v89, v87
	v_pk_add_f32 v[86:87], v[90:91], v[88:89]
	v_pk_mul_f32 v[88:89], v[76:77], v[76:77]
	v_pk_mul_f32 v[90:91], v[74:75], v[74:75]
	v_pk_add_f32 v[86:87], v[86:87], v[86:87] op_sel_hi:[0,1]
	v_pk_mov_b32 v[92:93], v[90:91], v[88:89] op_sel:[1,0]
	v_mov_b32_e32 v91, v89
	v_pk_add_f32 v[88:89], v[92:93], v[90:91]
	v_pk_fma_f32 v[90:91], v[70:71], v[70:71], v[0:1] op_sel_hi:[1,1,0]
	v_mul_f32_e32 v0, v72, v72
	v_pk_add_f32 v[88:89], v[88:89], v[88:89] op_sel_hi:[0,1]
	v_pk_fma_f32 v[92:93], v[72:73], v[72:73], v[0:1] op_sel_hi:[1,1,0]
	v_mul_f32_e32 v90, v66, v66
	v_mul_f32_e32 v92, v67, v67
	v_mul_f32_e32 v88, v68, v68
	v_mul_f32_e32 v86, v69, v69
	v_pk_add_f32 v[90:91], v[90:91], v[92:93]
	v_pk_add_f32 v[86:87], v[88:89], v[86:87]
	v_xor_b32_e32 v85, 16, v215
	v_pk_add_f32 v[86:87], v[90:91], v[86:87]
	s_nop 0
	v_add_f32_e32 v0, v86, v87
	v_and_b32_e32 v86, 64, v215
	v_add_u32_e32 v86, 64, v86
	v_cmp_lt_i32_e32 vcc, v85, v86
	s_nop 1
	v_cndmask_b32_e32 v85, v215, v85, vcc
	v_lshlrev_b32_e32 v85, 2, v85
	v_mov_b32_e32 v85, v0
	s_nop 1
	v_permlane16_swap_b32_e32 v85, v0
	s_waitcnt lgkmcnt(0)
	v_add_f32_e32 v0, v0, v85
	v_xor_b32_e32 v85, 32, v215
	v_cmp_lt_i32_e32 vcc, v85, v86
	s_nop 1
	v_cndmask_b32_e32 v85, v215, v85, vcc
	v_lshlrev_b32_e32 v85, 2, v85
	v_mov_b32_e32 v85, v0
	s_nop 1
	v_permlane32_swap_b32_e32 v85, v0
	s_waitcnt lgkmcnt(0)
	v_add_f32_e32 v0, v0, v85
	v_mul_f32_e32 v0, v174, v0
	v_mul_f32_e32 v0, v174, v0
	v_max_f32_e32 v85, v187, v187
	v_max_f32_e32 v187, v85, v0

.LBB0_289:
	v_pk_mul_f32 v[70:71], v[48:49], v[48:49]
	v_pk_mul_f32 v[72:73], v[46:47], v[46:47]
	v_mul_f32_e32 v0, v38, v38
	v_pk_mov_b32 v[74:75], v[72:73], v[70:71] op_sel:[1,0]
	v_mov_b32_e32 v73, v71
	v_pk_add_f32 v[70:71], v[74:75], v[72:73]
	v_pk_mul_f32 v[72:73], v[44:45], v[44:45]
	v_pk_mul_f32 v[74:75], v[42:43], v[42:43]
	v_pk_add_f32 v[70:71], v[70:71], v[70:71] op_sel_hi:[0,1]
	v_pk_mov_b32 v[76:77], v[74:75], v[72:73] op_sel:[1,0]
	v_mov_b32_e32 v75, v73
	v_pk_add_f32 v[72:73], v[76:77], v[74:75]
	v_pk_fma_f32 v[74:75], v[38:39], v[38:39], v[0:1] op_sel_hi:[1,1,0]
	v_mul_f32_e32 v0, v40, v40
	v_pk_add_f32 v[72:73], v[72:73], v[72:73] op_sel_hi:[0,1]
	v_pk_fma_f32 v[76:77], v[40:41], v[40:41], v[0:1] op_sel_hi:[1,1,0]
	v_mul_f32_e32 v74, v34, v34
	v_mul_f32_e32 v76, v35, v35
	v_mul_f32_e32 v72, v36, v36
	v_mul_f32_e32 v70, v37, v37
	v_pk_add_f32 v[74:75], v[74:75], v[76:77]
	v_pk_add_f32 v[70:71], v[72:73], v[70:71]
	v_xor_b32_e32 v69, 16, v215
	v_pk_add_f32 v[70:71], v[74:75], v[70:71]
	s_nop 0
	v_add_f32_e32 v0, v70, v71
	v_and_b32_e32 v70, 64, v215
	v_add_u32_e32 v70, 64, v70
	v_cmp_lt_i32_e32 vcc, v69, v70
	s_nop 1
	v_cndmask_b32_e32 v69, v215, v69, vcc
	v_lshlrev_b32_e32 v69, 2, v69
	v_mov_b32_e32 v69, v0
	s_nop 1
	v_permlane16_swap_b32_e32 v69, v0
	s_waitcnt lgkmcnt(0)
	v_add_f32_e32 v0, v0, v69
	v_xor_b32_e32 v69, 32, v215
	v_cmp_lt_i32_e32 vcc, v69, v70
	s_nop 1
	v_cndmask_b32_e32 v69, v215, v69, vcc
	v_lshlrev_b32_e32 v69, 2, v69
	v_mov_b32_e32 v69, v0
	s_nop 1
	v_permlane32_swap_b32_e32 v69, v0
	s_waitcnt lgkmcnt(0)
	v_add_f32_e32 v0, v0, v69
	v_mul_f32_e32 v0, v174, v0
	v_mul_f32_e32 v0, v174, v0
	v_max_f32_e32 v69, v187, v187
	v_max_f32_e32 v187, v69, v0

.LBB0_305:
	v_pk_mul_f32 v[38:39], v[32:33], v[32:33]
	v_pk_mul_f32 v[40:41], v[30:31], v[30:31]
	v_mul_f32_e32 v0, v22, v22
	v_pk_mov_b32 v[42:43], v[40:41], v[38:39] op_sel:[1,0]
	v_mov_b32_e32 v41, v39
	v_pk_add_f32 v[38:39], v[42:43], v[40:41]
	v_pk_mul_f32 v[40:41], v[28:29], v[28:29]
	v_pk_mul_f32 v[42:43], v[26:27], v[26:27]
	v_pk_add_f32 v[38:39], v[38:39], v[38:39] op_sel_hi:[0,1]
	v_pk_mov_b32 v[44:45], v[42:43], v[40:41] op_sel:[1,0]
	v_mov_b32_e32 v43, v41
	v_pk_add_f32 v[40:41], v[44:45], v[42:43]
	v_pk_fma_f32 v[42:43], v[22:23], v[22:23], v[0:1] op_sel_hi:[1,1,0]
	v_mul_f32_e32 v0, v24, v24
	v_pk_add_f32 v[40:41], v[40:41], v[40:41] op_sel_hi:[0,1]
	v_pk_fma_f32 v[44:45], v[24:25], v[24:25], v[0:1] op_sel_hi:[1,1,0]
	v_mul_f32_e32 v42, v18, v18
	v_mul_f32_e32 v44, v19, v19
	v_mul_f32_e32 v40, v20, v20
	v_mul_f32_e32 v38, v21, v21
	v_pk_add_f32 v[42:43], v[42:43], v[44:45]
	v_pk_add_f32 v[38:39], v[40:41], v[38:39]
	v_xor_b32_e32 v37, 16, v215
	v_pk_add_f32 v[38:39], v[42:43], v[38:39]
	s_nop 0
	v_add_f32_e32 v0, v38, v39
	v_and_b32_e32 v38, 64, v215
	v_add_u32_e32 v38, 64, v38
	v_cmp_lt_i32_e32 vcc, v37, v38
	s_nop 1
	v_cndmask_b32_e32 v37, v215, v37, vcc
	v_lshlrev_b32_e32 v37, 2, v37
	v_mov_b32_e32 v37, v0
	s_nop 1
	v_permlane16_swap_b32_e32 v37, v0
	s_waitcnt lgkmcnt(0)
	v_add_f32_e32 v0, v0, v37
	v_xor_b32_e32 v37, 32, v215
	v_cmp_lt_i32_e32 vcc, v37, v38
	s_nop 1
	v_cndmask_b32_e32 v37, v215, v37, vcc
	v_lshlrev_b32_e32 v37, 2, v37
	v_mov_b32_e32 v37, v0
	s_nop 1
	v_permlane32_swap_b32_e32 v37, v0
	s_waitcnt lgkmcnt(0)
	v_add_f32_e32 v0, v0, v37
	v_mul_f32_e32 v0, v174, v0
	v_mul_f32_e32 v0, v174, v0
	v_max_f32_e32 v37, v187, v187
	v_max_f32_e32 v187, v37, v0

.LBB0_317:
	s_andn2_b64 vcc, exec, s[2:3]
	s_cbranch_vccnz .LBB0_329
	s_and_b64 vcc, exec, s[10:11]
	s_cbranch_vccnz .LBB0_320
	v_pk_mul_f32 v[22:23], v[16:17], v[16:17]
	v_pk_mul_f32 v[24:25], v[14:15], v[14:15]
	v_mul_f32_e32 v0, v2, v2
	v_pk_mov_b32 v[26:27], v[24:25], v[22:23] op_sel:[1,0]
	v_mov_b32_e32 v25, v23
	v_pk_add_f32 v[22:23], v[26:27], v[24:25]
	v_pk_mul_f32 v[24:25], v[12:13], v[12:13]
	v_pk_mul_f32 v[26:27], v[10:11], v[10:11]
	v_mul_f32_e32 v21, v3, v3
	v_pk_mov_b32 v[28:29], v[26:27], v[24:25] op_sel:[1,0]
	v_mov_b32_e32 v27, v25
	v_pk_add_f32 v[24:25], v[28:29], v[26:27]
	v_pk_add_f32 v[22:23], v[22:23], v[22:23] op_sel:[0,1] op_sel_hi:[1,0]
	v_pk_add_f32 v[24:25], v[24:25], v[24:25] op_sel:[0,1] op_sel_hi:[1,0]
	v_mov_b32_e32 v23, v0
	v_mov_b32_e32 v25, v21
	v_mul_f32_e32 v0, v7, v7
	v_mul_f32_e32 v26, v4, v4
	v_pk_add_f32 v[22:23], v[22:23], v[24:25]
	v_pk_fma_f32 v[24:25], v[6:7], v[6:7], v[0:1] op_sel_hi:[1,1,0]
	v_mul_f32_e32 v0, v9, v9
	v_mul_f32_e32 v28, v5, v5
	v_mov_b32_e32 v25, v26
	v_pk_fma_f32 v[26:27], v[8:9], v[8:9], v[0:1] op_sel_hi:[1,1,0]
	v_xor_b32_e32 v21, 16, v215
	v_mov_b32_e32 v27, v28
	v_pk_add_f32 v[24:25], v[24:25], v[26:27]
	s_nop 0
	v_pk_add_f32 v[22:23], v[22:23], v[24:25]
	s_nop 0
	v_add_f32_e32 v0, v22, v23
	v_and_b32_e32 v22, 64, v215
	v_add_u32_e32 v22, 64, v22
	v_cmp_lt_i32_e32 vcc, v21, v22
	s_nop 1
	v_cndmask_b32_e32 v21, v215, v21, vcc
	v_lshlrev_b32_e32 v21, 2, v21
	v_mov_b32_e32 v21, v0
	s_nop 1
	v_permlane16_swap_b32_e32 v21, v0
	s_waitcnt lgkmcnt(0)
	v_add_f32_e32 v0, v0, v21
	v_xor_b32_e32 v21, 32, v215
	v_cmp_lt_i32_e32 vcc, v21, v22
	s_nop 1
	v_cndmask_b32_e32 v21, v215, v21, vcc
	v_lshlrev_b32_e32 v21, 2, v21
	v_mov_b32_e32 v21, v0
	s_nop 1
	v_permlane32_swap_b32_e32 v21, v0
	s_waitcnt lgkmcnt(0)
	v_add_f32_e32 v0, v0, v21
	v_fmamk_f32 v0, v0, 0x3c800000, v212
	v_mul_f32_e32 v21, 0x4b800000, v0
	v_cmp_gt_f32_e32 vcc, s40, v0
	s_nop 1
	v_cndmask_b32_e32 v0, v0, v21, vcc
	v_rsq_f32_e32 v0, v0
	s_nop 0
	v_mul_f32_e32 v21, 0x45800000, v0
	v_cndmask_b32_e32 v0, v0, v21, vcc
	v_pk_mul_f32 v[14:15], v[14:15], v[0:1] op_sel_hi:[1,0]
	v_pk_mul_f32 v[16:17], v[16:17], v[0:1] op_sel_hi:[1,0]
	v_pk_mul_f32 v[10:11], v[10:11], v[0:1] op_sel_hi:[1,0]
	v_pk_mul_f32 v[12:13], v[12:13], v[0:1] op_sel_hi:[1,0]
	v_pk_mul_f32 v[6:7], v[6:7], v[0:1] op_sel_hi:[1,0]
	v_pk_mul_f32 v[8:9], v[8:9], v[0:1] op_sel_hi:[1,0]
	v_pk_mul_f32 v[2:3], v[2:3], v[0:1] op_sel_hi:[1,0]
	v_pk_mul_f32 v[4:5], v[4:5], v[0:1] op_sel_hi:[1,0]
	s_waitcnt vmcnt(0)
	v_pk_mul_f32 v[16:17], v[64:65], v[16:17]
	v_pk_mul_f32 v[14:15], v[62:63], v[14:15]
	v_pk_mul_f32 v[12:13], v[60:61], v[12:13]
	v_pk_mul_f32 v[10:11], v[58:59], v[10:11]
	v_pk_mul_f32 v[8:9], v[56:57], v[8:9]
	v_pk_mul_f32 v[6:7], v[54:55], v[6:7]
	v_pk_mul_f32 v[4:5], v[52:53], v[4:5]
	v_pk_mul_f32 v[2:3], v[50:51], v[2:3]

.LBB0_322:
	v_readlane_b32 s84, v254, 61
	v_readlane_b32 s85, v254, 62
	s_andn2_b64 vcc, exec, s[26:27]
	s_cbranch_vccnz .LBB0_324
	v_pk_mul_f32 v[22:23], v[16:17], v[16:17]
	v_pk_mul_f32 v[24:25], v[14:15], v[14:15]
	v_mul_f32_e32 v0, v6, v6
	v_pk_mov_b32 v[26:27], v[24:25], v[22:23] op_sel:[1,0]
	v_mov_b32_e32 v25, v23
	v_pk_add_f32 v[22:23], v[26:27], v[24:25]
	v_pk_mul_f32 v[24:25], v[12:13], v[12:13]
	v_pk_mul_f32 v[26:27], v[10:11], v[10:11]
	v_pk_add_f32 v[22:23], v[22:23], v[22:23] op_sel_hi:[0,1]
	v_pk_mov_b32 v[28:29], v[26:27], v[24:25] op_sel:[1,0]
	v_mov_b32_e32 v27, v25
	v_pk_add_f32 v[24:25], v[28:29], v[26:27]
	v_pk_fma_f32 v[26:27], v[6:7], v[6:7], v[0:1] op_sel_hi:[1,1,0]
	v_mul_f32_e32 v0, v8, v8
	v_pk_add_f32 v[24:25], v[24:25], v[24:25] op_sel_hi:[0,1]
	v_pk_fma_f32 v[28:29], v[8:9], v[8:9], v[0:1] op_sel_hi:[1,1,0]
	v_mul_f32_e32 v26, v2, v2
	v_mul_f32_e32 v28, v3, v3
	v_mul_f32_e32 v24, v4, v4
	v_mul_f32_e32 v22, v5, v5
	v_pk_add_f32 v[26:27], v[26:27], v[28:29]
	v_pk_add_f32 v[22:23], v[24:25], v[22:23]
	v_xor_b32_e32 v21, 16, v215
	v_pk_add_f32 v[22:23], v[26:27], v[22:23]
	s_nop 0
	v_add_f32_e32 v0, v22, v23
	v_and_b32_e32 v22, 64, v215
	v_add_u32_e32 v22, 64, v22
	v_cmp_lt_i32_e32 vcc, v21, v22
	s_nop 1
	v_cndmask_b32_e32 v21, v215, v21, vcc
	v_lshlrev_b32_e32 v21, 2, v21
	v_mov_b32_e32 v21, v0
	s_nop 1
	v_permlane16_swap_b32_e32 v21, v0
	s_waitcnt lgkmcnt(0)
	v_add_f32_e32 v0, v0, v21
	v_xor_b32_e32 v21, 32, v215
	v_cmp_lt_i32_e32 vcc, v21, v22
	s_nop 1
	v_cndmask_b32_e32 v21, v215, v21, vcc
	v_lshlrev_b32_e32 v21, 2, v21
	v_mov_b32_e32 v21, v0
	s_nop 1
	v_permlane32_swap_b32_e32 v21, v0
	s_waitcnt lgkmcnt(0)
	v_add_f32_e32 v0, v0, v21
	v_mul_f32_e32 v0, v174, v0
	v_mul_f32_e32 v0, v174, v0
	v_max_f32_e32 v21, v187, v187
	v_max_f32_e32 v187, v21, v0

.LBB0_339:
	v_pk_mul_f32 v[180:181], v[144:145], v[144:145]
	v_pk_mul_f32 v[188:189], v[142:143], v[142:143]
	v_mul_f32_e32 v0, v130, v130
	v_pk_mov_b32 v[190:191], v[188:189], v[180:181] op_sel:[1,0]
	v_mov_b32_e32 v189, v181
	v_pk_add_f32 v[180:181], v[190:191], v[188:189]
	v_pk_mul_f32 v[188:189], v[140:141], v[140:141]
	v_pk_mul_f32 v[190:191], v[138:139], v[138:139]
	v_mul_f32_e32 v179, v131, v131
	v_pk_mov_b32 v[192:193], v[190:191], v[188:189] op_sel:[1,0]
	v_mov_b32_e32 v191, v189
	v_pk_add_f32 v[188:189], v[192:193], v[190:191]
	v_pk_add_f32 v[180:181], v[180:181], v[180:181] op_sel:[0,1] op_sel_hi:[1,0]
	v_pk_add_f32 v[188:189], v[188:189], v[188:189] op_sel:[0,1] op_sel_hi:[1,0]
	v_mov_b32_e32 v181, v0
	v_mov_b32_e32 v189, v179
	v_mul_f32_e32 v0, v135, v135
	v_pk_add_f32 v[180:181], v[180:181], v[188:189]
	v_pk_fma_f32 v[188:189], v[134:135], v[134:135], v[0:1] op_sel_hi:[1,1,0]
	v_mul_f32_e32 v0, v137, v137
	v_mul_f32_e32 v187, v132, v132
	v_mul_f32_e32 v192, v133, v133
	v_pk_fma_f32 v[190:191], v[136:137], v[136:137], v[0:1] op_sel_hi:[1,1,0]
	v_mov_b32_e32 v189, v187
	v_mov_b32_e32 v191, v192
	v_pk_add_f32 v[188:189], v[188:189], v[190:191]
	v_xor_b32_e32 v179, 16, v215
	v_pk_add_f32 v[180:181], v[180:181], v[188:189]
	s_nop 0
	v_add_f32_e32 v0, v180, v181
	v_and_b32_e32 v180, 64, v215
	v_add_u32_e32 v180, 64, v180
	v_cmp_lt_i32_e32 vcc, v179, v180
	s_nop 1
	v_cndmask_b32_e32 v179, v215, v179, vcc
	v_lshlrev_b32_e32 v179, 2, v179
	v_mov_b32_e32 v179, v0
	s_nop 1
	v_permlane16_swap_b32_e32 v179, v0
	s_waitcnt lgkmcnt(0)
	v_add_f32_e32 v0, v0, v179
	v_xor_b32_e32 v179, 32, v215
	v_cmp_lt_i32_e32 vcc, v179, v180
	s_nop 1
	v_cndmask_b32_e32 v179, v215, v179, vcc
	v_lshlrev_b32_e32 v179, 2, v179
	v_mov_b32_e32 v179, v0
	s_nop 1
	v_permlane32_swap_b32_e32 v179, v0
	s_waitcnt lgkmcnt(0)
	v_add_f32_e32 v0, v0, v179
	v_fmamk_f32 v0, v0, 0x3c800000, v212
	v_mul_f32_e32 v179, 0x4b800000, v0
	v_cmp_gt_f32_e32 vcc, s40, v0
	s_nop 1
	v_cndmask_b32_e32 v0, v0, v179, vcc
	v_rsq_f32_e32 v0, v0
	s_nop 0
	v_mul_f32_e32 v179, 0x45800000, v0
	v_cndmask_b32_e32 v0, v0, v179, vcc
	v_pk_mul_f32 v[142:143], v[142:143], v[0:1] op_sel_hi:[1,0]
	v_pk_mul_f32 v[144:145], v[144:145], v[0:1] op_sel_hi:[1,0]
	v_pk_mul_f32 v[138:139], v[138:139], v[0:1] op_sel_hi:[1,0]
	v_pk_mul_f32 v[140:141], v[140:141], v[0:1] op_sel_hi:[1,0]
	v_pk_mul_f32 v[134:135], v[134:135], v[0:1] op_sel_hi:[1,0]
	v_pk_mul_f32 v[136:137], v[136:137], v[0:1] op_sel_hi:[1,0]
	v_pk_mul_f32 v[130:131], v[130:131], v[0:1] op_sel_hi:[1,0]
	v_pk_mul_f32 v[132:133], v[132:133], v[0:1] op_sel_hi:[1,0]
	s_waitcnt vmcnt(0)
	v_pk_mul_f32 v[144:145], v[64:65], v[144:145]
	v_pk_mul_f32 v[142:143], v[62:63], v[142:143]
	v_pk_mul_f32 v[140:141], v[60:61], v[140:141]
	v_pk_mul_f32 v[138:139], v[58:59], v[138:139]
	v_pk_mul_f32 v[136:137], v[56:57], v[136:137]
	v_pk_mul_f32 v[134:135], v[54:55], v[134:135]
	v_pk_mul_f32 v[132:133], v[52:53], v[132:133]
	v_pk_mul_f32 v[130:131], v[50:51], v[130:131]
	s_andn2_b64 vcc, exec, s[84:85]
	s_cbranch_vccnz .LBB0_208

.LBB0_342:
	v_pk_mul_f32 v[134:135], v[128:129], v[128:129]
	v_pk_mul_f32 v[136:137], v[126:127], v[126:127]
	v_mul_f32_e32 v0, v114, v114
	v_pk_mov_b32 v[138:139], v[136:137], v[134:135] op_sel:[1,0]
	v_mov_b32_e32 v137, v135
	v_pk_add_f32 v[134:135], v[138:139], v[136:137]
	v_pk_mul_f32 v[136:137], v[124:125], v[124:125]
	v_pk_mul_f32 v[138:139], v[122:123], v[122:123]
	v_mul_f32_e32 v133, v115, v115
	v_pk_mov_b32 v[140:141], v[138:139], v[136:137] op_sel:[1,0]
	v_mov_b32_e32 v139, v137
	v_pk_add_f32 v[136:137], v[140:141], v[138:139]
	v_pk_add_f32 v[134:135], v[134:135], v[134:135] op_sel:[0,1] op_sel_hi:[1,0]
	v_pk_add_f32 v[136:137], v[136:137], v[136:137] op_sel:[0,1] op_sel_hi:[1,0]
	v_mov_b32_e32 v135, v0
	v_mov_b32_e32 v137, v133
	v_mul_f32_e32 v0, v119, v119
	v_mul_f32_e32 v138, v116, v116
	v_pk_add_f32 v[134:135], v[134:135], v[136:137]
	v_pk_fma_f32 v[136:137], v[118:119], v[118:119], v[0:1] op_sel_hi:[1,1,0]
	v_mul_f32_e32 v0, v121, v121
	v_mul_f32_e32 v140, v117, v117
	v_mov_b32_e32 v137, v138
	v_pk_fma_f32 v[138:139], v[120:121], v[120:121], v[0:1] op_sel_hi:[1,1,0]
	v_xor_b32_e32 v133, 16, v215
	v_mov_b32_e32 v139, v140
	v_pk_add_f32 v[136:137], v[136:137], v[138:139]
	s_nop 0
	v_pk_add_f32 v[134:135], v[134:135], v[136:137]
	s_nop 0
	v_add_f32_e32 v0, v134, v135
	v_and_b32_e32 v134, 64, v215
	v_add_u32_e32 v134, 64, v134
	v_cmp_lt_i32_e32 vcc, v133, v134
	s_nop 1
	v_cndmask_b32_e32 v133, v215, v133, vcc
	v_lshlrev_b32_e32 v133, 2, v133
	v_mov_b32_e32 v133, v0
	s_nop 1
	v_permlane16_swap_b32_e32 v133, v0
	s_waitcnt lgkmcnt(0)
	v_add_f32_e32 v0, v0, v133
	v_xor_b32_e32 v133, 32, v215
	v_cmp_lt_i32_e32 vcc, v133, v134
	s_nop 1
	v_cndmask_b32_e32 v133, v215, v133, vcc
	v_lshlrev_b32_e32 v133, 2, v133
	v_mov_b32_e32 v133, v0
	s_nop 1
	v_permlane32_swap_b32_e32 v133, v0
	s_waitcnt lgkmcnt(0)
	v_add_f32_e32 v0, v0, v133
	v_fmamk_f32 v0, v0, 0x3c800000, v212
	v_mul_f32_e32 v133, 0x4b800000, v0
	v_cmp_gt_f32_e32 vcc, s40, v0
	s_nop 1
	v_cndmask_b32_e32 v0, v0, v133, vcc
	v_rsq_f32_e32 v0, v0
	s_nop 0
	v_mul_f32_e32 v133, 0x45800000, v0
	v_cndmask_b32_e32 v0, v0, v133, vcc
	v_pk_mul_f32 v[126:127], v[126:127], v[0:1] op_sel_hi:[1,0]
	v_pk_mul_f32 v[128:129], v[128:129], v[0:1] op_sel_hi:[1,0]
	v_pk_mul_f32 v[122:123], v[122:123], v[0:1] op_sel_hi:[1,0]
	v_pk_mul_f32 v[124:125], v[124:125], v[0:1] op_sel_hi:[1,0]
	v_pk_mul_f32 v[118:119], v[118:119], v[0:1] op_sel_hi:[1,0]
	v_pk_mul_f32 v[120:121], v[120:121], v[0:1] op_sel_hi:[1,0]
	v_pk_mul_f32 v[114:115], v[114:115], v[0:1] op_sel_hi:[1,0]
	v_pk_mul_f32 v[116:117], v[116:117], v[0:1] op_sel_hi:[1,0]
	s_waitcnt vmcnt(0)
	v_pk_mul_f32 v[128:129], v[64:65], v[128:129]
	v_pk_mul_f32 v[126:127], v[62:63], v[126:127]
	v_pk_mul_f32 v[124:125], v[60:61], v[124:125]
	v_pk_mul_f32 v[122:123], v[58:59], v[122:123]
	v_pk_mul_f32 v[120:121], v[56:57], v[120:121]
	v_pk_mul_f32 v[118:119], v[54:55], v[118:119]
	v_pk_mul_f32 v[116:117], v[52:53], v[116:117]
	v_pk_mul_f32 v[114:115], v[50:51], v[114:115]
	s_andn2_b64 vcc, exec, s[84:85]
	s_cbranch_vccnz .LBB0_223

.LBB0_344:
	v_pk_mul_f32 v[118:119], v[112:113], v[112:113]
	v_pk_mul_f32 v[120:121], v[110:111], v[110:111]
	v_mul_f32_e32 v0, v98, v98
	v_pk_mov_b32 v[122:123], v[120:121], v[118:119] op_sel:[1,0]
	v_mov_b32_e32 v121, v119
	v_pk_add_f32 v[118:119], v[122:123], v[120:121]
	v_pk_mul_f32 v[120:121], v[108:109], v[108:109]
	v_pk_mul_f32 v[122:123], v[106:107], v[106:107]
	v_mul_f32_e32 v117, v99, v99
	v_pk_mov_b32 v[124:125], v[122:123], v[120:121] op_sel:[1,0]
	v_mov_b32_e32 v123, v121
	v_pk_add_f32 v[120:121], v[124:125], v[122:123]
	v_pk_add_f32 v[118:119], v[118:119], v[118:119] op_sel:[0,1] op_sel_hi:[1,0]
	v_pk_add_f32 v[120:121], v[120:121], v[120:121] op_sel:[0,1] op_sel_hi:[1,0]
	v_mov_b32_e32 v119, v0
	v_mov_b32_e32 v121, v117
	v_mul_f32_e32 v0, v103, v103
	v_mul_f32_e32 v122, v100, v100
	v_pk_add_f32 v[118:119], v[118:119], v[120:121]
	v_pk_fma_f32 v[120:121], v[102:103], v[102:103], v[0:1] op_sel_hi:[1,1,0]
	v_mul_f32_e32 v0, v105, v105
	v_mul_f32_e32 v124, v101, v101
	v_mov_b32_e32 v121, v122
	v_pk_fma_f32 v[122:123], v[104:105], v[104:105], v[0:1] op_sel_hi:[1,1,0]
	v_xor_b32_e32 v117, 16, v215
	v_mov_b32_e32 v123, v124
	v_pk_add_f32 v[120:121], v[120:121], v[122:123]
	s_nop 0
	v_pk_add_f32 v[118:119], v[118:119], v[120:121]
	s_nop 0
	v_add_f32_e32 v0, v118, v119
	v_and_b32_e32 v118, 64, v215
	v_add_u32_e32 v118, 64, v118
	v_cmp_lt_i32_e32 vcc, v117, v118
	s_nop 1
	v_cndmask_b32_e32 v117, v215, v117, vcc
	v_lshlrev_b32_e32 v117, 2, v117
	v_mov_b32_e32 v117, v0
	s_nop 1
	v_permlane16_swap_b32_e32 v117, v0
	s_waitcnt lgkmcnt(0)
	v_add_f32_e32 v0, v0, v117
	v_xor_b32_e32 v117, 32, v215
	v_cmp_lt_i32_e32 vcc, v117, v118
	s_nop 1
	v_cndmask_b32_e32 v117, v215, v117, vcc
	v_lshlrev_b32_e32 v117, 2, v117
	v_mov_b32_e32 v117, v0
	s_nop 1
	v_permlane32_swap_b32_e32 v117, v0
	s_waitcnt lgkmcnt(0)
	v_add_f32_e32 v0, v0, v117
	v_fmamk_f32 v0, v0, 0x3c800000, v212
	v_mul_f32_e32 v117, 0x4b800000, v0
	v_cmp_gt_f32_e32 vcc, s40, v0
	s_nop 1
	v_cndmask_b32_e32 v0, v0, v117, vcc
	v_rsq_f32_e32 v0, v0
	s_nop 0
	v_mul_f32_e32 v117, 0x45800000, v0
	v_cndmask_b32_e32 v0, v0, v117, vcc
	v_pk_mul_f32 v[110:111], v[110:111], v[0:1] op_sel_hi:[1,0]
	v_pk_mul_f32 v[112:113], v[112:113], v[0:1] op_sel_hi:[1,0]
	v_pk_mul_f32 v[106:107], v[106:107], v[0:1] op_sel_hi:[1,0]
	v_pk_mul_f32 v[108:109], v[108:109], v[0:1] op_sel_hi:[1,0]
	v_pk_mul_f32 v[102:103], v[102:103], v[0:1] op_sel_hi:[1,0]
	v_pk_mul_f32 v[104:105], v[104:105], v[0:1] op_sel_hi:[1,0]
	v_pk_mul_f32 v[98:99], v[98:99], v[0:1] op_sel_hi:[1,0]
	v_pk_mul_f32 v[100:101], v[100:101], v[0:1] op_sel_hi:[1,0]
	s_waitcnt vmcnt(0)
	v_pk_mul_f32 v[112:113], v[64:65], v[112:113]
	v_pk_mul_f32 v[110:111], v[62:63], v[110:111]
	v_pk_mul_f32 v[108:109], v[60:61], v[108:109]
	v_pk_mul_f32 v[106:107], v[58:59], v[106:107]
	v_pk_mul_f32 v[104:105], v[56:57], v[104:105]
	v_pk_mul_f32 v[102:103], v[54:55], v[102:103]
	v_pk_mul_f32 v[100:101], v[52:53], v[100:101]
	v_pk_mul_f32 v[98:99], v[50:51], v[98:99]
	s_andn2_b64 vcc, exec, s[84:85]
	s_cbranch_vccnz .LBB0_240

.LBB0_346:
	v_pk_mul_f32 v[102:103], v[96:97], v[96:97]
	v_pk_mul_f32 v[104:105], v[94:95], v[94:95]
	v_mul_f32_e32 v0, v82, v82
	v_pk_mov_b32 v[106:107], v[104:105], v[102:103] op_sel:[1,0]
	v_mov_b32_e32 v105, v103
	v_pk_add_f32 v[102:103], v[106:107], v[104:105]
	v_pk_mul_f32 v[104:105], v[92:93], v[92:93]
	v_pk_mul_f32 v[106:107], v[90:91], v[90:91]
	v_mul_f32_e32 v101, v83, v83
	v_pk_mov_b32 v[108:109], v[106:107], v[104:105] op_sel:[1,0]
	v_mov_b32_e32 v107, v105
	v_pk_add_f32 v[104:105], v[108:109], v[106:107]
	v_pk_add_f32 v[102:103], v[102:103], v[102:103] op_sel:[0,1] op_sel_hi:[1,0]
	v_pk_add_f32 v[104:105], v[104:105], v[104:105] op_sel:[0,1] op_sel_hi:[1,0]
	v_mov_b32_e32 v103, v0
	v_mov_b32_e32 v105, v101
	v_mul_f32_e32 v0, v87, v87
	v_mul_f32_e32 v106, v84, v84
	v_pk_add_f32 v[102:103], v[102:103], v[104:105]
	v_pk_fma_f32 v[104:105], v[86:87], v[86:87], v[0:1] op_sel_hi:[1,1,0]
	v_mul_f32_e32 v0, v89, v89
	v_mul_f32_e32 v108, v85, v85
	v_mov_b32_e32 v105, v106
	v_pk_fma_f32 v[106:107], v[88:89], v[88:89], v[0:1] op_sel_hi:[1,1,0]
	v_xor_b32_e32 v101, 16, v215
	v_mov_b32_e32 v107, v108
	v_pk_add_f32 v[104:105], v[104:105], v[106:107]
	s_nop 0
	v_pk_add_f32 v[102:103], v[102:103], v[104:105]
	s_nop 0
	v_add_f32_e32 v0, v102, v103
	v_and_b32_e32 v102, 64, v215
	v_add_u32_e32 v102, 64, v102
	v_cmp_lt_i32_e32 vcc, v101, v102
	s_nop 1
	v_cndmask_b32_e32 v101, v215, v101, vcc
	v_lshlrev_b32_e32 v101, 2, v101
	v_mov_b32_e32 v101, v0
	s_nop 1
	v_permlane16_swap_b32_e32 v101, v0
	s_waitcnt lgkmcnt(0)
	v_add_f32_e32 v0, v0, v101
	v_xor_b32_e32 v101, 32, v215
	v_cmp_lt_i32_e32 vcc, v101, v102
	s_nop 1
	v_cndmask_b32_e32 v101, v215, v101, vcc
	v_lshlrev_b32_e32 v101, 2, v101
	v_mov_b32_e32 v101, v0
	s_nop 1
	v_permlane32_swap_b32_e32 v101, v0
	s_waitcnt lgkmcnt(0)
	v_add_f32_e32 v0, v0, v101
	v_fmamk_f32 v0, v0, 0x3c800000, v212
	v_mul_f32_e32 v101, 0x4b800000, v0
	v_cmp_gt_f32_e32 vcc, s40, v0
	s_nop 1
	v_cndmask_b32_e32 v0, v0, v101, vcc
	v_rsq_f32_e32 v0, v0
	s_nop 0
	v_mul_f32_e32 v101, 0x45800000, v0
	v_cndmask_b32_e32 v0, v0, v101, vcc
	v_pk_mul_f32 v[94:95], v[94:95], v[0:1] op_sel_hi:[1,0]
	v_pk_mul_f32 v[96:97], v[96:97], v[0:1] op_sel_hi:[1,0]
	v_pk_mul_f32 v[90:91], v[90:91], v[0:1] op_sel_hi:[1,0]
	v_pk_mul_f32 v[92:93], v[92:93], v[0:1] op_sel_hi:[1,0]
	v_pk_mul_f32 v[86:87], v[86:87], v[0:1] op_sel_hi:[1,0]
	v_pk_mul_f32 v[88:89], v[88:89], v[0:1] op_sel_hi:[1,0]
	v_pk_mul_f32 v[82:83], v[82:83], v[0:1] op_sel_hi:[1,0]
	v_pk_mul_f32 v[84:85], v[84:85], v[0:1] op_sel_hi:[1,0]
	s_waitcnt vmcnt(0)
	v_pk_mul_f32 v[96:97], v[64:65], v[96:97]
	v_pk_mul_f32 v[94:95], v[62:63], v[94:95]
	v_pk_mul_f32 v[92:93], v[60:61], v[92:93]
	v_pk_mul_f32 v[90:91], v[58:59], v[90:91]
	v_pk_mul_f32 v[88:89], v[56:57], v[88:89]
	v_pk_mul_f32 v[86:87], v[54:55], v[86:87]
	v_pk_mul_f32 v[84:85], v[52:53], v[84:85]
	v_pk_mul_f32 v[82:83], v[50:51], v[82:83]
	s_andn2_b64 vcc, exec, s[84:85]
	s_cbranch_vccnz .LBB0_256

.LBB0_348:
	v_pk_mul_f32 v[86:87], v[80:81], v[80:81]
	v_pk_mul_f32 v[88:89], v[78:79], v[78:79]
	v_mul_f32_e32 v0, v66, v66
	v_pk_mov_b32 v[90:91], v[88:89], v[86:87] op_sel:[1,0]
	v_mov_b32_e32 v89, v87
	v_pk_add_f32 v[86:87], v[90:91], v[88:89]
	v_pk_mul_f32 v[88:89], v[76:77], v[76:77]
	v_pk_mul_f32 v[90:91], v[74:75], v[74:75]
	v_mul_f32_e32 v85, v67, v67
	v_pk_mov_b32 v[92:93], v[90:91], v[88:89] op_sel:[1,0]
	v_mov_b32_e32 v91, v89
	v_pk_add_f32 v[88:89], v[92:93], v[90:91]
	v_pk_add_f32 v[86:87], v[86:87], v[86:87] op_sel:[0,1] op_sel_hi:[1,0]
	v_pk_add_f32 v[88:89], v[88:89], v[88:89] op_sel:[0,1] op_sel_hi:[1,0]
	v_mov_b32_e32 v87, v0
	v_mov_b32_e32 v89, v85
	v_mul_f32_e32 v0, v71, v71
	v_mul_f32_e32 v90, v68, v68
	v_pk_add_f32 v[86:87], v[86:87], v[88:89]
	v_pk_fma_f32 v[88:89], v[70:71], v[70:71], v[0:1] op_sel_hi:[1,1,0]
	v_mul_f32_e32 v0, v73, v73
	v_mul_f32_e32 v92, v69, v69
	v_mov_b32_e32 v89, v90
	v_pk_fma_f32 v[90:91], v[72:73], v[72:73], v[0:1] op_sel_hi:[1,1,0]
	v_xor_b32_e32 v85, 16, v215
	v_mov_b32_e32 v91, v92
	v_pk_add_f32 v[88:89], v[88:89], v[90:91]
	s_nop 0
	v_pk_add_f32 v[86:87], v[86:87], v[88:89]
	s_nop 0
	v_add_f32_e32 v0, v86, v87
	v_and_b32_e32 v86, 64, v215
	v_add_u32_e32 v86, 64, v86
	v_cmp_lt_i32_e32 vcc, v85, v86
	s_nop 1
	v_cndmask_b32_e32 v85, v215, v85, vcc
	v_lshlrev_b32_e32 v85, 2, v85
	v_mov_b32_e32 v85, v0
	s_nop 1
	v_permlane16_swap_b32_e32 v85, v0
	s_waitcnt lgkmcnt(0)
	v_add_f32_e32 v0, v0, v85
	v_xor_b32_e32 v85, 32, v215
	v_cmp_lt_i32_e32 vcc, v85, v86
	s_nop 1
	v_cndmask_b32_e32 v85, v215, v85, vcc
	v_lshlrev_b32_e32 v85, 2, v85
	v_mov_b32_e32 v85, v0
	s_nop 1
	v_permlane32_swap_b32_e32 v85, v0
	s_waitcnt lgkmcnt(0)
	v_add_f32_e32 v0, v0, v85
	v_fmamk_f32 v0, v0, 0x3c800000, v212
	v_mul_f32_e32 v85, 0x4b800000, v0
	v_cmp_gt_f32_e32 vcc, s40, v0
	s_nop 1
	v_cndmask_b32_e32 v0, v0, v85, vcc
	v_rsq_f32_e32 v0, v0
	s_nop 0
	v_mul_f32_e32 v85, 0x45800000, v0
	v_cndmask_b32_e32 v0, v0, v85, vcc
	v_pk_mul_f32 v[78:79], v[78:79], v[0:1] op_sel_hi:[1,0]
	v_pk_mul_f32 v[80:81], v[80:81], v[0:1] op_sel_hi:[1,0]
	v_pk_mul_f32 v[74:75], v[74:75], v[0:1] op_sel_hi:[1,0]
	v_pk_mul_f32 v[76:77], v[76:77], v[0:1] op_sel_hi:[1,0]
	v_pk_mul_f32 v[70:71], v[70:71], v[0:1] op_sel_hi:[1,0]
	v_pk_mul_f32 v[72:73], v[72:73], v[0:1] op_sel_hi:[1,0]
	v_pk_mul_f32 v[66:67], v[66:67], v[0:1] op_sel_hi:[1,0]
	v_pk_mul_f32 v[68:69], v[68:69], v[0:1] op_sel_hi:[1,0]
	s_waitcnt vmcnt(0)
	v_pk_mul_f32 v[80:81], v[64:65], v[80:81]
	v_pk_mul_f32 v[78:79], v[62:63], v[78:79]
	v_pk_mul_f32 v[76:77], v[60:61], v[76:77]
	v_pk_mul_f32 v[74:75], v[58:59], v[74:75]
	v_pk_mul_f32 v[72:73], v[56:57], v[72:73]
	v_pk_mul_f32 v[70:71], v[54:55], v[70:71]
	v_pk_mul_f32 v[68:69], v[52:53], v[68:69]
	v_pk_mul_f32 v[66:67], v[50:51], v[66:67]
	s_andn2_b64 vcc, exec, s[84:85]
	s_cbranch_vccnz .LBB0_272

.LBB0_350:
	v_pk_mul_f32 v[70:71], v[48:49], v[48:49]
	v_pk_mul_f32 v[72:73], v[46:47], v[46:47]
	v_mul_f32_e32 v0, v34, v34
	v_pk_mov_b32 v[74:75], v[72:73], v[70:71] op_sel:[1,0]
	v_mov_b32_e32 v73, v71
	v_pk_add_f32 v[70:71], v[74:75], v[72:73]
	v_pk_mul_f32 v[72:73], v[44:45], v[44:45]
	v_pk_mul_f32 v[74:75], v[42:43], v[42:43]
	v_mul_f32_e32 v69, v35, v35
	v_pk_mov_b32 v[76:77], v[74:75], v[72:73] op_sel:[1,0]
	v_mov_b32_e32 v75, v73
	v_pk_add_f32 v[72:73], v[76:77], v[74:75]
	v_pk_add_f32 v[70:71], v[70:71], v[70:71] op_sel:[0,1] op_sel_hi:[1,0]
	v_pk_add_f32 v[72:73], v[72:73], v[72:73] op_sel:[0,1] op_sel_hi:[1,0]
	v_mov_b32_e32 v71, v0
	v_mov_b32_e32 v73, v69
	v_mul_f32_e32 v0, v39, v39
	v_mul_f32_e32 v74, v36, v36
	v_pk_add_f32 v[70:71], v[70:71], v[72:73]
	v_pk_fma_f32 v[72:73], v[38:39], v[38:39], v[0:1] op_sel_hi:[1,1,0]
	v_mul_f32_e32 v0, v41, v41
	v_mul_f32_e32 v76, v37, v37
	v_mov_b32_e32 v73, v74
	v_pk_fma_f32 v[74:75], v[40:41], v[40:41], v[0:1] op_sel_hi:[1,1,0]
	v_xor_b32_e32 v69, 16, v215
	v_mov_b32_e32 v75, v76
	v_pk_add_f32 v[72:73], v[72:73], v[74:75]
	s_nop 0
	v_pk_add_f32 v[70:71], v[70:71], v[72:73]
	s_nop 0
	v_add_f32_e32 v0, v70, v71
	v_and_b32_e32 v70, 64, v215
	v_add_u32_e32 v70, 64, v70
	v_cmp_lt_i32_e32 vcc, v69, v70
	s_nop 1
	v_cndmask_b32_e32 v69, v215, v69, vcc
	v_lshlrev_b32_e32 v69, 2, v69
	v_mov_b32_e32 v69, v0
	s_nop 1
	v_permlane16_swap_b32_e32 v69, v0
	s_waitcnt lgkmcnt(0)
	v_add_f32_e32 v0, v0, v69
	v_xor_b32_e32 v69, 32, v215
	v_cmp_lt_i32_e32 vcc, v69, v70
	s_nop 1
	v_cndmask_b32_e32 v69, v215, v69, vcc
	v_lshlrev_b32_e32 v69, 2, v69
	v_mov_b32_e32 v69, v0
	s_nop 1
	v_permlane32_swap_b32_e32 v69, v0
	s_waitcnt lgkmcnt(0)
	v_add_f32_e32 v0, v0, v69
	v_fmamk_f32 v0, v0, 0x3c800000, v212
	v_mul_f32_e32 v69, 0x4b800000, v0
	v_cmp_gt_f32_e32 vcc, s40, v0
	s_nop 1
	v_cndmask_b32_e32 v0, v0, v69, vcc
	v_rsq_f32_e32 v0, v0
	s_nop 0
	v_mul_f32_e32 v69, 0x45800000, v0
	v_cndmask_b32_e32 v0, v0, v69, vcc
	v_pk_mul_f32 v[46:47], v[46:47], v[0:1] op_sel_hi:[1,0]
	v_pk_mul_f32 v[48:49], v[48:49], v[0:1] op_sel_hi:[1,0]
	v_pk_mul_f32 v[42:43], v[42:43], v[0:1] op_sel_hi:[1,0]
	v_pk_mul_f32 v[44:45], v[44:45], v[0:1] op_sel_hi:[1,0]
	v_pk_mul_f32 v[38:39], v[38:39], v[0:1] op_sel_hi:[1,0]
	v_pk_mul_f32 v[40:41], v[40:41], v[0:1] op_sel_hi:[1,0]
	v_pk_mul_f32 v[34:35], v[34:35], v[0:1] op_sel_hi:[1,0]
	v_pk_mul_f32 v[36:37], v[36:37], v[0:1] op_sel_hi:[1,0]
	s_waitcnt vmcnt(0)
	v_pk_mul_f32 v[48:49], v[64:65], v[48:49]
	v_pk_mul_f32 v[46:47], v[62:63], v[46:47]
	v_pk_mul_f32 v[44:45], v[60:61], v[44:45]
	v_pk_mul_f32 v[42:43], v[58:59], v[42:43]
	v_pk_mul_f32 v[40:41], v[56:57], v[40:41]
	v_pk_mul_f32 v[38:39], v[54:55], v[38:39]
	v_pk_mul_f32 v[36:37], v[52:53], v[36:37]
	v_pk_mul_f32 v[34:35], v[50:51], v[34:35]
	s_andn2_b64 vcc, exec, s[84:85]
	s_cbranch_vccnz .LBB0_288

.LBB0_352:
	v_pk_mul_f32 v[38:39], v[32:33], v[32:33]
	v_pk_mul_f32 v[40:41], v[30:31], v[30:31]
	v_mul_f32_e32 v0, v18, v18
	v_pk_mov_b32 v[42:43], v[40:41], v[38:39] op_sel:[1,0]
	v_mov_b32_e32 v41, v39
	v_pk_add_f32 v[38:39], v[42:43], v[40:41]
	v_pk_mul_f32 v[40:41], v[28:29], v[28:29]
	v_pk_mul_f32 v[42:43], v[26:27], v[26:27]
	v_mul_f32_e32 v37, v19, v19
	v_pk_mov_b32 v[44:45], v[42:43], v[40:41] op_sel:[1,0]
	v_mov_b32_e32 v43, v41
	v_pk_add_f32 v[40:41], v[44:45], v[42:43]
	v_pk_add_f32 v[38:39], v[38:39], v[38:39] op_sel:[0,1] op_sel_hi:[1,0]
	v_pk_add_f32 v[40:41], v[40:41], v[40:41] op_sel:[0,1] op_sel_hi:[1,0]
	v_mov_b32_e32 v39, v0
	v_mov_b32_e32 v41, v37
	v_mul_f32_e32 v0, v23, v23
	v_mul_f32_e32 v42, v20, v20
	v_pk_add_f32 v[38:39], v[38:39], v[40:41]
	v_pk_fma_f32 v[40:41], v[22:23], v[22:23], v[0:1] op_sel_hi:[1,1,0]
	v_mul_f32_e32 v0, v25, v25
	v_mul_f32_e32 v44, v21, v21
	v_mov_b32_e32 v41, v42
	v_pk_fma_f32 v[42:43], v[24:25], v[24:25], v[0:1] op_sel_hi:[1,1,0]
	v_xor_b32_e32 v37, 16, v215
	v_mov_b32_e32 v43, v44
	v_pk_add_f32 v[40:41], v[40:41], v[42:43]
	s_nop 0
	v_pk_add_f32 v[38:39], v[38:39], v[40:41]
	s_nop 0
	v_add_f32_e32 v0, v38, v39
	v_and_b32_e32 v38, 64, v215
	v_add_u32_e32 v38, 64, v38
	v_cmp_lt_i32_e32 vcc, v37, v38
	s_nop 1
	v_cndmask_b32_e32 v37, v215, v37, vcc
	v_lshlrev_b32_e32 v37, 2, v37
	v_mov_b32_e32 v37, v0
	s_nop 1
	v_permlane16_swap_b32_e32 v37, v0
	s_waitcnt lgkmcnt(0)
	v_add_f32_e32 v0, v0, v37
	v_xor_b32_e32 v37, 32, v215
	v_cmp_lt_i32_e32 vcc, v37, v38
	s_nop 1
	v_cndmask_b32_e32 v37, v215, v37, vcc
	v_lshlrev_b32_e32 v37, 2, v37
	v_mov_b32_e32 v37, v0
	s_nop 1
	v_permlane32_swap_b32_e32 v37, v0
	s_waitcnt lgkmcnt(0)
	v_add_f32_e32 v0, v0, v37
	v_fmamk_f32 v0, v0, 0x3c800000, v212
	v_mul_f32_e32 v37, 0x4b800000, v0
	v_cmp_gt_f32_e32 vcc, s40, v0
	s_nop 1
	v_cndmask_b32_e32 v0, v0, v37, vcc
	v_rsq_f32_e32 v0, v0
	s_nop 0
	v_mul_f32_e32 v37, 0x45800000, v0
	v_cndmask_b32_e32 v0, v0, v37, vcc
	v_pk_mul_f32 v[30:31], v[30:31], v[0:1] op_sel_hi:[1,0]
	v_pk_mul_f32 v[32:33], v[32:33], v[0:1] op_sel_hi:[1,0]
	v_pk_mul_f32 v[26:27], v[26:27], v[0:1] op_sel_hi:[1,0]
	v_pk_mul_f32 v[28:29], v[28:29], v[0:1] op_sel_hi:[1,0]
	v_pk_mul_f32 v[22:23], v[22:23], v[0:1] op_sel_hi:[1,0]
	v_pk_mul_f32 v[24:25], v[24:25], v[0:1] op_sel_hi:[1,0]
	v_pk_mul_f32 v[18:19], v[18:19], v[0:1] op_sel_hi:[1,0]
	v_pk_mul_f32 v[20:21], v[20:21], v[0:1] op_sel_hi:[1,0]
	s_waitcnt vmcnt(0)
	v_pk_mul_f32 v[32:33], v[64:65], v[32:33]
	v_pk_mul_f32 v[30:31], v[62:63], v[30:31]
	v_pk_mul_f32 v[28:29], v[60:61], v[28:29]
	v_pk_mul_f32 v[26:27], v[58:59], v[26:27]
	v_pk_mul_f32 v[24:25], v[56:57], v[24:25]
	v_pk_mul_f32 v[22:23], v[54:55], v[22:23]
	v_pk_mul_f32 v[20:21], v[52:53], v[20:21]
	v_pk_mul_f32 v[18:19], v[50:51], v[18:19]
	s_andn2_b64 vcc, exec, s[84:85]
	s_cbranch_vccnz .LBB0_304

.LBB0_653:
	v_and_b32_e32 v145, 64, v215
	v_xor_b32_e32 v0, 16, v215
	v_add_u32_e32 v145, 64, v145
	v_cmp_lt_i32_e32 vcc, v0, v145
	v_mul_f32_e32 v147, v129, v129
	v_fmac_f32_e32 v147, v128, v128
	v_cndmask_b32_e32 v0, v215, v0, vcc
	v_lshlrev_b32_e32 v146, 2, v0
	v_xor_b32_e32 v0, 32, v215
	v_cmp_lt_i32_e32 vcc, v0, v145
	s_ashr_i32 s25, s24, 31
	s_lshl_b64 s[2:3], s[24:25], 8
	v_cndmask_b32_e32 v0, v215, v0, vcc
	v_lshlrev_b32_e32 v145, 2, v0
	v_mul_f32_e32 v0, v127, v127
	v_fmac_f32_e32 v0, v126, v126
	v_add_f32_e32 v0, v0, v147
	v_mul_f32_e32 v147, v123, v123
	v_fmac_f32_e32 v147, v122, v122
	v_add_f32_e32 v0, v0, v147
	v_mul_f32_e32 v147, v125, v125
	v_fmac_f32_e32 v147, v124, v124
	v_cvt_pk_bf16_f32 v126, v126, v127
	v_cvt_pk_bf16_f32 v127, v128, v129
	v_cvt_pk_bf16_f32 v129, v124, v125
	v_mul_f32_e32 v124, v119, v119
	v_mul_f32_e32 v125, v121, v121
	v_fmac_f32_e32 v124, v118, v118
	v_fmac_f32_e32 v125, v120, v120
	v_add_f32_e32 v124, v124, v125
	v_mul_f32_e32 v125, v115, v115
	v_fmac_f32_e32 v125, v114, v114
	v_add_f32_e32 v124, v124, v125
	v_mul_f32_e32 v125, v117, v117
	v_fmac_f32_e32 v125, v116, v116
	v_add_f32_e32 v0, v147, v0
	v_add_f32_e32 v124, v125, v124
	v_add_f32_e32 v124, v0, v124
	v_lshl_add_u64 v[142:143], s[2:3], 0, v[136:137]
	v_mov_b32_e32 v125, v124
	s_nop 1
	v_permlane16_swap_b32_e32 v125, v124
	s_lshl_b32 s24, s22, 8
	v_lshlrev_b64 v[148:149], 11, v[142:143]
	s_ashr_i32 s25, s24, 31
	v_cvt_pk_bf16_f32 v128, v122, v123
	v_lshl_add_u64 v[122:123], s[76:77], 0, v[148:149]
	v_lshl_add_u64 v[122:123], s[24:25], 1, v[122:123]
	s_lshl_b32 s68, s36, 1
	v_lshl_add_u64 v[122:123], v[122:123], 0, s[68:69]
	v_lshlrev_b32_e32 v0, 1, v134
	v_lshl_add_u64 v[148:149], v[122:123], 0, v[0:1]
	v_cvt_pk_bf16_f32 v122, v118, v119
	s_waitcnt lgkmcnt(0)
	v_add_f32_e32 v118, v124, v125
	v_mov_b32_e32 v119, v118
	s_nop 1
	v_permlane32_swap_b32_e32 v119, v118
	s_lshl_b32 s4, s22, 2
	s_ashr_i32 s5, s4, 31
	v_cvt_pk_bf16_f32 v123, v120, v121
	v_cvt_pk_bf16_f32 v124, v114, v115
	v_cvt_pk_bf16_f32 v125, v116, v117
	global_store_dwordx4 v[148:149], v[126:129], off
	global_store_dwordx4 v[148:149], v[122:125], off offset:256
	s_and_saveexec_b64 s[2:3], s[0:1]
	s_cbranch_execz .LBB0_655
	v_lshlrev_b64 v[114:115], 6, v[142:143]
	v_lshl_add_u64 v[114:115], s[80:81], 0, v[114:115]
	v_lshl_add_u64 v[114:115], s[4:5], 2, v[114:115]
	s_lshl_b32 s26, s35, 2
	s_mov_b32 s27, s69
	s_waitcnt lgkmcnt(0)
	v_add_f32_e32 v116, v118, v119
	v_lshl_add_u64 v[114:115], v[114:115], 0, s[26:27]
	global_store_dword v[114:115], v116, off
.LBB0_655:
	s_or_b64 exec, exec, s[2:3]
	v_mul_f32_e32 v118, v111, v111
	s_waitcnt lgkmcnt(0)
	v_mul_f32_e32 v119, v113, v113
	v_fmac_f32_e32 v118, v110, v110
	v_fmac_f32_e32 v119, v112, v112
	v_add_f32_e32 v118, v118, v119
	v_mul_f32_e32 v119, v107, v107
	v_fmac_f32_e32 v119, v106, v106
	v_add_f32_e32 v118, v118, v119
	v_mul_f32_e32 v119, v109, v109
	v_fmac_f32_e32 v119, v108, v108
	v_cvt_pk_bf16_f32 v110, v110, v111
	v_cvt_pk_bf16_f32 v111, v112, v113
	v_cvt_pk_bf16_f32 v113, v108, v109
	v_mul_f32_e32 v108, v103, v103
	v_mul_f32_e32 v109, v105, v105
	v_fmac_f32_e32 v108, v102, v102
	v_fmac_f32_e32 v109, v104, v104
	v_add_f32_e32 v108, v108, v109
	v_mul_f32_e32 v109, v99, v99
	v_fmac_f32_e32 v109, v98, v98
	v_add_f32_e32 v108, v108, v109
	v_mul_f32_e32 v109, v101, v101
	v_fmac_f32_e32 v109, v100, v100
	v_add_f32_e32 v118, v119, v118
	v_add_f32_e32 v108, v109, v108
	v_add_f32_e32 v108, v118, v108
	v_or_b32_e32 v114, 16, v142
	v_mov_b32_e32 v115, v143
	v_mov_b32_e32 v109, v108
	s_nop 1
	v_permlane16_swap_b32_e32 v109, v108
	v_lshlrev_b64 v[116:117], 11, v[114:115]
	v_cvt_pk_bf16_f32 v112, v106, v107
	v_lshl_add_u64 v[106:107], s[76:77], 0, v[116:117]
	v_lshl_add_u64 v[106:107], s[24:25], 1, v[106:107]
	v_lshl_add_u64 v[106:107], v[106:107], 0, s[68:69]
	v_lshl_add_u64 v[116:117], v[106:107], 0, v[0:1]
	v_cvt_pk_bf16_f32 v106, v102, v103
	s_waitcnt lgkmcnt(0)
	v_add_f32_e32 v102, v108, v109
	v_mov_b32_e32 v103, v102
	s_nop 1
	v_permlane32_swap_b32_e32 v103, v102
	v_cvt_pk_bf16_f32 v107, v104, v105
	v_cvt_pk_bf16_f32 v108, v98, v99
	v_cvt_pk_bf16_f32 v109, v100, v101
	global_store_dwordx4 v[116:117], v[110:113], off
	global_store_dwordx4 v[116:117], v[106:109], off offset:256
	s_and_saveexec_b64 s[2:3], s[0:1]
	s_cbranch_execz .LBB0_657
	v_lshlrev_b64 v[98:99], 6, v[114:115]
	v_lshl_add_u64 v[98:99], s[80:81], 0, v[98:99]
	v_lshl_add_u64 v[98:99], s[4:5], 2, v[98:99]
	s_lshl_b32 s26, s35, 2
	s_mov_b32 s27, s69
	s_waitcnt lgkmcnt(0)
	v_add_f32_e32 v100, v102, v103
	v_lshl_add_u64 v[98:99], v[98:99], 0, s[26:27]
	global_store_dword v[98:99], v100, off
.LBB0_657:
	s_or_b64 exec, exec, s[2:3]
	v_mul_f32_e32 v102, v95, v95
	s_waitcnt lgkmcnt(0)
	v_mul_f32_e32 v103, v97, v97
	v_fmac_f32_e32 v102, v94, v94
	v_fmac_f32_e32 v103, v96, v96
	v_add_f32_e32 v102, v102, v103
	v_mul_f32_e32 v103, v91, v91
	v_fmac_f32_e32 v103, v90, v90
	v_add_f32_e32 v102, v102, v103
	v_mul_f32_e32 v103, v93, v93
	v_fmac_f32_e32 v103, v92, v92
	v_cvt_pk_bf16_f32 v94, v94, v95
	v_cvt_pk_bf16_f32 v95, v96, v97
	v_cvt_pk_bf16_f32 v97, v92, v93
	v_mul_f32_e32 v92, v87, v87
	v_mul_f32_e32 v93, v89, v89
	v_fmac_f32_e32 v92, v86, v86
	v_fmac_f32_e32 v93, v88, v88
	v_add_f32_e32 v92, v92, v93
	v_mul_f32_e32 v93, v83, v83
	v_fmac_f32_e32 v93, v82, v82
	v_add_f32_e32 v92, v92, v93
	v_mul_f32_e32 v93, v85, v85
	v_fmac_f32_e32 v93, v84, v84
	v_add_f32_e32 v102, v103, v102
	v_add_f32_e32 v92, v93, v92
	v_add_f32_e32 v92, v102, v92
	v_or_b32_e32 v98, 32, v142
	v_mov_b32_e32 v99, v143
	v_mov_b32_e32 v93, v92
	s_nop 1
	v_permlane16_swap_b32_e32 v93, v92
	v_lshlrev_b64 v[100:101], 11, v[98:99]
	v_cvt_pk_bf16_f32 v96, v90, v91
	v_lshl_add_u64 v[90:91], s[76:77], 0, v[100:101]
	v_lshl_add_u64 v[90:91], s[24:25], 1, v[90:91]
	v_lshl_add_u64 v[90:91], v[90:91], 0, s[68:69]
	v_lshl_add_u64 v[100:101], v[90:91], 0, v[0:1]
	v_cvt_pk_bf16_f32 v90, v86, v87
	s_waitcnt lgkmcnt(0)
	v_add_f32_e32 v86, v92, v93
	v_mov_b32_e32 v87, v86
	s_nop 1
	v_permlane32_swap_b32_e32 v87, v86
	v_cvt_pk_bf16_f32 v91, v88, v89
	v_cvt_pk_bf16_f32 v92, v82, v83
	v_cvt_pk_bf16_f32 v93, v84, v85
	global_store_dwordx4 v[100:101], v[94:97], off
	global_store_dwordx4 v[100:101], v[90:93], off offset:256
	s_and_saveexec_b64 s[2:3], s[0:1]
	s_cbranch_execz .LBB0_659
	v_lshlrev_b64 v[82:83], 6, v[98:99]
	v_lshl_add_u64 v[82:83], s[80:81], 0, v[82:83]
	v_lshl_add_u64 v[82:83], s[4:5], 2, v[82:83]
	s_lshl_b32 s26, s35, 2
	s_mov_b32 s27, s69
	s_waitcnt lgkmcnt(0)
	v_add_f32_e32 v84, v86, v87
	v_lshl_add_u64 v[82:83], v[82:83], 0, s[26:27]
	global_store_dword v[82:83], v84, off
.LBB0_659:
	s_or_b64 exec, exec, s[2:3]
	v_mul_f32_e32 v86, v79, v79
	s_waitcnt lgkmcnt(0)
	v_mul_f32_e32 v87, v81, v81
	v_fmac_f32_e32 v86, v78, v78
	v_fmac_f32_e32 v87, v80, v80
	v_add_f32_e32 v86, v86, v87
	v_mul_f32_e32 v87, v75, v75
	v_fmac_f32_e32 v87, v74, v74
	v_add_f32_e32 v86, v86, v87
	v_mul_f32_e32 v87, v77, v77
	v_fmac_f32_e32 v87, v76, v76
	v_cvt_pk_bf16_f32 v78, v78, v79
	v_cvt_pk_bf16_f32 v79, v80, v81
	v_cvt_pk_bf16_f32 v81, v76, v77
	v_mul_f32_e32 v76, v71, v71
	v_mul_f32_e32 v77, v73, v73
	v_fmac_f32_e32 v76, v70, v70
	v_fmac_f32_e32 v77, v72, v72
	v_add_f32_e32 v76, v76, v77
	v_mul_f32_e32 v77, v67, v67
	v_fmac_f32_e32 v77, v66, v66
	v_add_f32_e32 v76, v76, v77
	v_mul_f32_e32 v77, v69, v69
	v_fmac_f32_e32 v77, v68, v68
	v_add_f32_e32 v86, v87, v86
	v_add_f32_e32 v76, v77, v76
	v_add_f32_e32 v76, v86, v76
	v_or_b32_e32 v82, 48, v142
	v_mov_b32_e32 v83, v143
	v_mov_b32_e32 v77, v76
	s_nop 1
	v_permlane16_swap_b32_e32 v77, v76
	v_lshlrev_b64 v[84:85], 11, v[82:83]
	v_cvt_pk_bf16_f32 v80, v74, v75
	v_lshl_add_u64 v[74:75], s[76:77], 0, v[84:85]
	v_lshl_add_u64 v[74:75], s[24:25], 1, v[74:75]
	v_lshl_add_u64 v[74:75], v[74:75], 0, s[68:69]
	v_lshl_add_u64 v[84:85], v[74:75], 0, v[0:1]
	v_cvt_pk_bf16_f32 v74, v70, v71
	s_waitcnt lgkmcnt(0)
	v_add_f32_e32 v70, v76, v77
	v_mov_b32_e32 v71, v70
	s_nop 1
	v_permlane32_swap_b32_e32 v71, v70
	v_cvt_pk_bf16_f32 v75, v72, v73
	v_cvt_pk_bf16_f32 v76, v66, v67
	v_cvt_pk_bf16_f32 v77, v68, v69
	global_store_dwordx4 v[84:85], v[78:81], off
	global_store_dwordx4 v[84:85], v[74:77], off offset:256
	s_and_saveexec_b64 s[2:3], s[0:1]
	s_cbranch_execz .LBB0_661
	v_lshlrev_b64 v[66:67], 6, v[82:83]
	v_lshl_add_u64 v[66:67], s[80:81], 0, v[66:67]
	v_lshl_add_u64 v[66:67], s[4:5], 2, v[66:67]
	s_lshl_b32 s26, s35, 2
	s_mov_b32 s27, s69
	s_waitcnt lgkmcnt(0)
	v_add_f32_e32 v68, v70, v71
	v_lshl_add_u64 v[66:67], v[66:67], 0, s[26:27]
	global_store_dword v[66:67], v68, off
.LBB0_661:
	s_or_b64 exec, exec, s[2:3]
	v_mul_f32_e32 v70, v63, v63
	s_waitcnt lgkmcnt(0)
	v_mul_f32_e32 v71, v65, v65
	v_fmac_f32_e32 v70, v62, v62
	v_fmac_f32_e32 v71, v64, v64
	v_add_f32_e32 v70, v70, v71
	v_mul_f32_e32 v71, v59, v59
	v_fmac_f32_e32 v71, v58, v58
	v_add_f32_e32 v70, v70, v71
	v_mul_f32_e32 v71, v61, v61
	v_fmac_f32_e32 v71, v60, v60
	v_cvt_pk_bf16_f32 v62, v62, v63
	v_cvt_pk_bf16_f32 v63, v64, v65
	v_cvt_pk_bf16_f32 v65, v60, v61
	v_mul_f32_e32 v60, v55, v55
	v_mul_f32_e32 v61, v57, v57
	v_fmac_f32_e32 v60, v54, v54
	v_fmac_f32_e32 v61, v56, v56
	v_add_f32_e32 v60, v60, v61
	v_mul_f32_e32 v61, v51, v51
	v_fmac_f32_e32 v61, v50, v50
	v_add_f32_e32 v60, v60, v61
	v_mul_f32_e32 v61, v53, v53
	v_fmac_f32_e32 v61, v52, v52
	v_add_f32_e32 v70, v71, v70
	v_add_f32_e32 v60, v61, v60
	v_add_f32_e32 v60, v70, v60
	v_lshl_add_u64 v[66:67], v[142:143], 0, s[44:45]
	v_mov_b32_e32 v61, v60
	s_nop 1
	v_permlane16_swap_b32_e32 v61, v60
	v_lshlrev_b64 v[68:69], 11, v[66:67]
	v_cvt_pk_bf16_f32 v64, v58, v59
	v_lshl_add_u64 v[58:59], s[76:77], 0, v[68:69]
	v_lshl_add_u64 v[58:59], s[24:25], 1, v[58:59]
	v_lshl_add_u64 v[58:59], v[58:59], 0, s[68:69]
	v_lshl_add_u64 v[68:69], v[58:59], 0, v[0:1]
	v_cvt_pk_bf16_f32 v58, v54, v55
	s_waitcnt lgkmcnt(0)
	v_add_f32_e32 v54, v60, v61
	v_mov_b32_e32 v55, v54
	s_nop 1
	v_permlane32_swap_b32_e32 v55, v54
	v_cvt_pk_bf16_f32 v59, v56, v57
	v_cvt_pk_bf16_f32 v60, v50, v51
	v_cvt_pk_bf16_f32 v61, v52, v53
	global_store_dwordx4 v[68:69], v[62:65], off
	global_store_dwordx4 v[68:69], v[58:61], off offset:256
	s_and_saveexec_b64 s[2:3], s[0:1]
	s_cbranch_execz .LBB0_663
	v_lshlrev_b64 v[50:51], 6, v[66:67]
	v_lshl_add_u64 v[50:51], s[80:81], 0, v[50:51]
	v_lshl_add_u64 v[50:51], s[4:5], 2, v[50:51]
	s_lshl_b32 s26, s35, 2
	s_mov_b32 s27, s69
	s_waitcnt lgkmcnt(0)
	v_add_f32_e32 v52, v54, v55
	v_lshl_add_u64 v[50:51], v[50:51], 0, s[26:27]
	global_store_dword v[50:51], v52, off
.LBB0_663:
	s_or_b64 exec, exec, s[2:3]
	v_mul_f32_e32 v54, v47, v47
	s_waitcnt lgkmcnt(0)
	v_mul_f32_e32 v55, v49, v49
	v_fmac_f32_e32 v54, v46, v46
	v_fmac_f32_e32 v55, v48, v48
	v_add_f32_e32 v54, v54, v55
	v_mul_f32_e32 v55, v43, v43
	v_fmac_f32_e32 v55, v42, v42
	v_add_f32_e32 v54, v54, v55
	v_mul_f32_e32 v55, v45, v45
	v_fmac_f32_e32 v55, v44, v44
	v_cvt_pk_bf16_f32 v46, v46, v47
	v_cvt_pk_bf16_f32 v47, v48, v49
	v_cvt_pk_bf16_f32 v49, v44, v45
	v_mul_f32_e32 v44, v39, v39
	v_mul_f32_e32 v45, v41, v41
	v_fmac_f32_e32 v44, v38, v38
	v_fmac_f32_e32 v45, v40, v40
	v_add_f32_e32 v44, v44, v45
	v_mul_f32_e32 v45, v35, v35
	v_fmac_f32_e32 v45, v34, v34
	v_add_f32_e32 v44, v44, v45
	v_mul_f32_e32 v45, v37, v37
	v_fmac_f32_e32 v45, v36, v36
	v_add_f32_e32 v54, v55, v54
	v_add_f32_e32 v44, v45, v44
	s_mov_b64 s[2:3], 0x90
	v_add_f32_e32 v44, v54, v44
	v_lshl_add_u64 v[50:51], v[142:143], 0, s[2:3]
	v_mov_b32_e32 v45, v44
	s_nop 1
	v_permlane16_swap_b32_e32 v45, v44
	v_lshlrev_b64 v[52:53], 11, v[50:51]
	v_cvt_pk_bf16_f32 v48, v42, v43
	v_lshl_add_u64 v[42:43], s[76:77], 0, v[52:53]
	v_lshl_add_u64 v[42:43], s[24:25], 1, v[42:43]
	v_lshl_add_u64 v[42:43], v[42:43], 0, s[68:69]
	v_lshl_add_u64 v[52:53], v[42:43], 0, v[0:1]
	v_cvt_pk_bf16_f32 v42, v38, v39
	s_waitcnt lgkmcnt(0)
	v_add_f32_e32 v38, v44, v45
	v_mov_b32_e32 v39, v38
	s_nop 1
	v_permlane32_swap_b32_e32 v39, v38
	v_cvt_pk_bf16_f32 v43, v40, v41
	v_cvt_pk_bf16_f32 v44, v34, v35
	v_cvt_pk_bf16_f32 v45, v36, v37
	global_store_dwordx4 v[52:53], v[46:49], off
	global_store_dwordx4 v[52:53], v[42:45], off offset:256
	s_and_saveexec_b64 s[2:3], s[0:1]
	s_cbranch_execz .LBB0_665
	v_lshlrev_b64 v[34:35], 6, v[50:51]
	v_lshl_add_u64 v[34:35], s[80:81], 0, v[34:35]
	v_lshl_add_u64 v[34:35], s[4:5], 2, v[34:35]
	s_lshl_b32 s26, s35, 2
	s_mov_b32 s27, s69
	s_waitcnt lgkmcnt(0)
	v_add_f32_e32 v36, v38, v39
	v_lshl_add_u64 v[34:35], v[34:35], 0, s[26:27]
	global_store_dword v[34:35], v36, off
.LBB0_665:
	s_or_b64 exec, exec, s[2:3]
	v_mul_f32_e32 v38, v31, v31
	s_waitcnt lgkmcnt(0)
	v_mul_f32_e32 v39, v33, v33
	v_fmac_f32_e32 v38, v30, v30
	v_fmac_f32_e32 v39, v32, v32
	v_add_f32_e32 v38, v38, v39
	v_mul_f32_e32 v39, v27, v27
	v_fmac_f32_e32 v39, v26, v26
	v_add_f32_e32 v38, v38, v39
	v_mul_f32_e32 v39, v29, v29
	v_fmac_f32_e32 v39, v28, v28
	v_cvt_pk_bf16_f32 v30, v30, v31
	v_cvt_pk_bf16_f32 v31, v32, v33
	v_cvt_pk_bf16_f32 v33, v28, v29
	v_mul_f32_e32 v28, v23, v23
	v_mul_f32_e32 v29, v25, v25
	v_fmac_f32_e32 v28, v22, v22
	v_fmac_f32_e32 v29, v24, v24
	v_add_f32_e32 v28, v28, v29
	v_mul_f32_e32 v29, v19, v19
	v_fmac_f32_e32 v29, v18, v18
	v_add_f32_e32 v28, v28, v29
	v_mul_f32_e32 v29, v21, v21
	v_fmac_f32_e32 v29, v20, v20
	v_add_f32_e32 v38, v39, v38
	v_add_f32_e32 v28, v29, v28
	s_mov_b64 s[2:3], 0xa0
	v_add_f32_e32 v28, v38, v28
	v_lshl_add_u64 v[34:35], v[142:143], 0, s[2:3]
	v_mov_b32_e32 v29, v28
	s_nop 1
	v_permlane16_swap_b32_e32 v29, v28
	v_lshlrev_b64 v[36:37], 11, v[34:35]
	v_cvt_pk_bf16_f32 v32, v26, v27
	v_lshl_add_u64 v[26:27], s[76:77], 0, v[36:37]
	v_lshl_add_u64 v[26:27], s[24:25], 1, v[26:27]
	v_lshl_add_u64 v[26:27], v[26:27], 0, s[68:69]
	v_lshl_add_u64 v[36:37], v[26:27], 0, v[0:1]
	v_cvt_pk_bf16_f32 v26, v22, v23
	s_waitcnt lgkmcnt(0)
	v_add_f32_e32 v22, v28, v29
	v_mov_b32_e32 v23, v22
	s_nop 1
	v_permlane32_swap_b32_e32 v23, v22
	v_cvt_pk_bf16_f32 v27, v24, v25
	v_cvt_pk_bf16_f32 v28, v18, v19
	v_cvt_pk_bf16_f32 v29, v20, v21
	global_store_dwordx4 v[36:37], v[30:33], off
	global_store_dwordx4 v[36:37], v[26:29], off offset:256
	s_and_saveexec_b64 s[2:3], s[0:1]
	s_cbranch_execz .LBB0_667
	v_lshlrev_b64 v[18:19], 6, v[34:35]
	v_lshl_add_u64 v[18:19], s[80:81], 0, v[18:19]
	v_lshl_add_u64 v[18:19], s[4:5], 2, v[18:19]
	s_lshl_b32 s26, s35, 2
	s_mov_b32 s27, s69
	s_waitcnt lgkmcnt(0)
	v_add_f32_e32 v20, v22, v23
	v_lshl_add_u64 v[18:19], v[18:19], 0, s[26:27]
	global_store_dword v[18:19], v20, off
.LBB0_667:
	s_or_b64 exec, exec, s[2:3]
	v_mul_f32_e32 v22, v15, v15
	s_waitcnt lgkmcnt(0)
	v_mul_f32_e32 v23, v17, v17
	v_fmac_f32_e32 v22, v14, v14
	v_fmac_f32_e32 v23, v16, v16
	v_add_f32_e32 v22, v22, v23
	v_mul_f32_e32 v23, v11, v11
	v_fmac_f32_e32 v23, v10, v10
	v_add_f32_e32 v22, v22, v23
	v_mul_f32_e32 v23, v13, v13
	v_fmac_f32_e32 v23, v12, v12
	v_cvt_pk_bf16_f32 v14, v14, v15
	v_cvt_pk_bf16_f32 v15, v16, v17
	v_cvt_pk_bf16_f32 v17, v12, v13
	v_mul_f32_e32 v12, v7, v7
	v_mul_f32_e32 v13, v9, v9
	v_fmac_f32_e32 v12, v6, v6
	v_fmac_f32_e32 v13, v8, v8
	v_add_f32_e32 v12, v12, v13
	v_mul_f32_e32 v13, v3, v3
	v_fmac_f32_e32 v13, v2, v2
	v_add_f32_e32 v12, v12, v13
	v_mul_f32_e32 v13, v5, v5
	v_fmac_f32_e32 v13, v4, v4
	v_add_f32_e32 v22, v23, v22
	v_add_f32_e32 v12, v13, v12
	s_mov_b64 s[2:3], 0xb0
	v_add_f32_e32 v12, v22, v12
	v_lshl_add_u64 v[18:19], v[142:143], 0, s[2:3]
	v_mov_b32_e32 v13, v12
	s_nop 1
	v_permlane16_swap_b32_e32 v13, v12
	v_lshlrev_b64 v[20:21], 11, v[18:19]
	v_cvt_pk_bf16_f32 v16, v10, v11
	v_lshl_add_u64 v[10:11], s[76:77], 0, v[20:21]
	v_lshl_add_u64 v[10:11], s[24:25], 1, v[10:11]
	v_lshl_add_u64 v[10:11], v[10:11], 0, s[68:69]
	v_lshl_add_u64 v[20:21], v[10:11], 0, v[0:1]
	s_waitcnt lgkmcnt(0)
	v_add_f32_e32 v0, v12, v13
	v_cvt_pk_bf16_f32 v10, v6, v7
	v_mov_b32_e32 v6, v0
	s_nop 1
	v_permlane32_swap_b32_e32 v6, v0
	v_cvt_pk_bf16_f32 v11, v8, v9
	v_cvt_pk_bf16_f32 v12, v2, v3
	v_cvt_pk_bf16_f32 v13, v4, v5
	global_store_dwordx4 v[20:21], v[14:17], off
	global_store_dwordx4 v[20:21], v[10:13], off offset:256
	s_and_saveexec_b64 s[2:3], s[0:1]
	s_cbranch_execz .LBB0_669
	v_lshlrev_b64 v[2:3], 6, v[18:19]
	v_lshl_add_u64 v[2:3], s[80:81], 0, v[2:3]
	v_lshl_add_u64 v[2:3], s[4:5], 2, v[2:3]
	s_lshl_b32 s68, s35, 2
	s_waitcnt lgkmcnt(0)
	v_add_f32_e32 v0, v0, v6
	v_lshl_add_u64 v[2:3], v[2:3], 0, s[68:69]
	global_store_dword v[2:3], v0, off

.LBB0_852:
	v_and_b32_e32 v145, 64, v215
	v_xor_b32_e32 v0, 16, v215
	v_add_u32_e32 v145, 64, v145
	v_cmp_lt_i32_e32 vcc, v0, v145
	v_mul_f32_e32 v147, v129, v129
	v_fmac_f32_e32 v147, v128, v128
	v_cndmask_b32_e32 v0, v215, v0, vcc
	v_lshlrev_b32_e32 v146, 2, v0
	v_xor_b32_e32 v0, 32, v215
	v_cmp_lt_i32_e32 vcc, v0, v145
	s_ashr_i32 s17, s16, 31
	s_lshl_b64 s[2:3], s[16:17], 8
	v_cndmask_b32_e32 v0, v215, v0, vcc
	v_lshlrev_b32_e32 v145, 2, v0
	v_mul_f32_e32 v0, v127, v127
	v_fmac_f32_e32 v0, v126, v126
	v_add_f32_e32 v0, v0, v147
	v_mul_f32_e32 v147, v123, v123
	v_fmac_f32_e32 v147, v122, v122
	v_add_f32_e32 v0, v0, v147
	v_mul_f32_e32 v147, v125, v125
	v_fmac_f32_e32 v147, v124, v124
	v_cvt_pk_bf16_f32 v126, v126, v127
	v_cvt_pk_bf16_f32 v127, v128, v129
	v_cvt_pk_bf16_f32 v129, v124, v125
	v_mul_f32_e32 v124, v119, v119
	v_mul_f32_e32 v125, v121, v121
	v_fmac_f32_e32 v124, v118, v118
	v_fmac_f32_e32 v125, v120, v120
	v_add_f32_e32 v124, v124, v125
	v_mul_f32_e32 v125, v115, v115
	v_fmac_f32_e32 v125, v114, v114
	v_add_f32_e32 v124, v124, v125
	v_mul_f32_e32 v125, v117, v117
	v_fmac_f32_e32 v125, v116, v116
	v_add_f32_e32 v0, v147, v0
	v_add_f32_e32 v124, v125, v124
	v_add_f32_e32 v124, v0, v124
	v_lshl_add_u64 v[142:143], s[2:3], 0, v[136:137]
	v_readlane_b32 s2, v253, 59
	v_mov_b32_e32 v125, v124
	s_nop 1
	v_permlane16_swap_b32_e32 v125, v124
	s_lshl_b32 s18, s41, 8
	v_lshlrev_b64 v[148:149], 11, v[142:143]
	v_readlane_b32 s3, v253, 60
	s_ashr_i32 s19, s18, 31
	v_cvt_pk_bf16_f32 v128, v122, v123
	v_lshl_add_u64 v[122:123], s[2:3], 0, v[148:149]
	v_lshl_add_u64 v[122:123], s[18:19], 1, v[122:123]
	s_lshl_b32 s68, s30, 1
	v_lshl_add_u64 v[122:123], v[122:123], 0, s[68:69]
	v_lshlrev_b32_e32 v0, 1, v134
	v_lshl_add_u64 v[148:149], v[122:123], 0, v[0:1]
	v_cvt_pk_bf16_f32 v122, v118, v119
	s_waitcnt lgkmcnt(0)
	v_add_f32_e32 v118, v124, v125
	v_mov_b32_e32 v119, v118
	s_nop 1
	v_permlane32_swap_b32_e32 v119, v118
	s_lshl_b32 s16, s41, 2
	s_ashr_i32 s17, s16, 31
	v_cvt_pk_bf16_f32 v123, v120, v121
	v_cvt_pk_bf16_f32 v124, v114, v115
	v_cvt_pk_bf16_f32 v125, v116, v117
	global_store_dwordx4 v[148:149], v[126:129], off
	global_store_dwordx4 v[148:149], v[122:125], off offset:256
	s_and_saveexec_b64 s[2:3], s[0:1]
	s_cbranch_execz .LBB0_854
	v_readlane_b32 s20, v253, 57
	v_lshlrev_b64 v[114:115], 6, v[142:143]
	v_readlane_b32 s21, v253, 58
	s_waitcnt lgkmcnt(0)
	v_add_f32_e32 v116, v118, v119
	v_lshl_add_u64 v[114:115], s[20:21], 0, v[114:115]
	v_lshl_add_u64 v[114:115], s[16:17], 2, v[114:115]
	s_lshl_b32 s20, s29, 2
	s_mov_b32 s21, s69
	v_lshl_add_u64 v[114:115], v[114:115], 0, s[20:21]
	global_store_dword v[114:115], v116, off
.LBB0_854:
	s_or_b64 exec, exec, s[2:3]
	v_mul_f32_e32 v118, v111, v111
	s_waitcnt lgkmcnt(0)
	v_mul_f32_e32 v119, v113, v113
	v_fmac_f32_e32 v118, v110, v110
	v_fmac_f32_e32 v119, v112, v112
	v_add_f32_e32 v118, v118, v119
	v_mul_f32_e32 v119, v107, v107
	v_fmac_f32_e32 v119, v106, v106
	v_add_f32_e32 v118, v118, v119
	v_mul_f32_e32 v119, v109, v109
	v_fmac_f32_e32 v119, v108, v108
	v_cvt_pk_bf16_f32 v110, v110, v111
	v_cvt_pk_bf16_f32 v111, v112, v113
	v_cvt_pk_bf16_f32 v113, v108, v109
	v_mul_f32_e32 v108, v103, v103
	v_mul_f32_e32 v109, v105, v105
	v_fmac_f32_e32 v108, v102, v102
	v_fmac_f32_e32 v109, v104, v104
	v_add_f32_e32 v108, v108, v109
	v_mul_f32_e32 v109, v99, v99
	v_fmac_f32_e32 v109, v98, v98
	v_add_f32_e32 v108, v108, v109
	v_mul_f32_e32 v109, v101, v101
	v_fmac_f32_e32 v109, v100, v100
	v_add_f32_e32 v118, v119, v118
	v_add_f32_e32 v108, v109, v108
	v_add_f32_e32 v108, v118, v108
	v_or_b32_e32 v114, 16, v142
	v_mov_b32_e32 v115, v143
	v_readlane_b32 s2, v253, 59
	v_mov_b32_e32 v109, v108
	s_nop 1
	v_permlane16_swap_b32_e32 v109, v108
	v_lshlrev_b64 v[116:117], 11, v[114:115]
	v_readlane_b32 s3, v253, 60
	v_cvt_pk_bf16_f32 v112, v106, v107
	s_nop 0
	v_lshl_add_u64 v[106:107], s[2:3], 0, v[116:117]
	v_lshl_add_u64 v[106:107], s[18:19], 1, v[106:107]
	v_lshl_add_u64 v[106:107], v[106:107], 0, s[68:69]
	v_lshl_add_u64 v[116:117], v[106:107], 0, v[0:1]
	v_cvt_pk_bf16_f32 v106, v102, v103
	s_waitcnt lgkmcnt(0)
	v_add_f32_e32 v102, v108, v109
	v_mov_b32_e32 v103, v102
	s_nop 1
	v_permlane32_swap_b32_e32 v103, v102
	v_cvt_pk_bf16_f32 v107, v104, v105
	v_cvt_pk_bf16_f32 v108, v98, v99
	v_cvt_pk_bf16_f32 v109, v100, v101
	global_store_dwordx4 v[116:117], v[110:113], off
	global_store_dwordx4 v[116:117], v[106:109], off offset:256
	s_and_saveexec_b64 s[2:3], s[0:1]
	s_cbranch_execz .LBB0_856
	v_readlane_b32 s20, v253, 57
	v_lshlrev_b64 v[98:99], 6, v[114:115]
	v_readlane_b32 s21, v253, 58
	s_waitcnt lgkmcnt(0)
	v_add_f32_e32 v100, v102, v103
	v_lshl_add_u64 v[98:99], s[20:21], 0, v[98:99]
	v_lshl_add_u64 v[98:99], s[16:17], 2, v[98:99]
	s_lshl_b32 s20, s29, 2
	s_mov_b32 s21, s69
	v_lshl_add_u64 v[98:99], v[98:99], 0, s[20:21]
	global_store_dword v[98:99], v100, off
.LBB0_856:
	s_or_b64 exec, exec, s[2:3]
	v_mul_f32_e32 v102, v95, v95
	s_waitcnt lgkmcnt(0)
	v_mul_f32_e32 v103, v97, v97
	v_fmac_f32_e32 v102, v94, v94
	v_fmac_f32_e32 v103, v96, v96
	v_add_f32_e32 v102, v102, v103
	v_mul_f32_e32 v103, v91, v91
	v_fmac_f32_e32 v103, v90, v90
	v_add_f32_e32 v102, v102, v103
	v_mul_f32_e32 v103, v93, v93
	v_fmac_f32_e32 v103, v92, v92
	v_cvt_pk_bf16_f32 v94, v94, v95
	v_cvt_pk_bf16_f32 v95, v96, v97
	v_cvt_pk_bf16_f32 v97, v92, v93
	v_mul_f32_e32 v92, v87, v87
	v_mul_f32_e32 v93, v89, v89
	v_fmac_f32_e32 v92, v86, v86
	v_fmac_f32_e32 v93, v88, v88
	v_add_f32_e32 v92, v92, v93
	v_mul_f32_e32 v93, v83, v83
	v_fmac_f32_e32 v93, v82, v82
	v_add_f32_e32 v92, v92, v93
	v_mul_f32_e32 v93, v85, v85
	v_fmac_f32_e32 v93, v84, v84
	v_add_f32_e32 v102, v103, v102
	v_add_f32_e32 v92, v93, v92
	v_add_f32_e32 v92, v102, v92
	v_or_b32_e32 v98, 32, v142
	v_mov_b32_e32 v99, v143
	v_readlane_b32 s2, v253, 59
	v_mov_b32_e32 v93, v92
	s_nop 1
	v_permlane16_swap_b32_e32 v93, v92
	v_lshlrev_b64 v[100:101], 11, v[98:99]
	v_readlane_b32 s3, v253, 60
	v_cvt_pk_bf16_f32 v96, v90, v91
	s_nop 0
	v_lshl_add_u64 v[90:91], s[2:3], 0, v[100:101]
	v_lshl_add_u64 v[90:91], s[18:19], 1, v[90:91]
	v_lshl_add_u64 v[90:91], v[90:91], 0, s[68:69]
	v_lshl_add_u64 v[100:101], v[90:91], 0, v[0:1]
	v_cvt_pk_bf16_f32 v90, v86, v87
	s_waitcnt lgkmcnt(0)
	v_add_f32_e32 v86, v92, v93
	v_mov_b32_e32 v87, v86
	s_nop 1
	v_permlane32_swap_b32_e32 v87, v86
	v_cvt_pk_bf16_f32 v91, v88, v89
	v_cvt_pk_bf16_f32 v92, v82, v83
	v_cvt_pk_bf16_f32 v93, v84, v85
	global_store_dwordx4 v[100:101], v[94:97], off
	global_store_dwordx4 v[100:101], v[90:93], off offset:256
	s_and_saveexec_b64 s[2:3], s[0:1]
	s_cbranch_execz .LBB0_858
	v_readlane_b32 s20, v253, 57
	v_lshlrev_b64 v[82:83], 6, v[98:99]
	v_readlane_b32 s21, v253, 58
	s_waitcnt lgkmcnt(0)
	v_add_f32_e32 v84, v86, v87
	v_lshl_add_u64 v[82:83], s[20:21], 0, v[82:83]
	v_lshl_add_u64 v[82:83], s[16:17], 2, v[82:83]
	s_lshl_b32 s20, s29, 2
	s_mov_b32 s21, s69
	v_lshl_add_u64 v[82:83], v[82:83], 0, s[20:21]
	global_store_dword v[82:83], v84, off
.LBB0_858:
	s_or_b64 exec, exec, s[2:3]
	v_mul_f32_e32 v86, v79, v79
	s_waitcnt lgkmcnt(0)
	v_mul_f32_e32 v87, v81, v81
	v_fmac_f32_e32 v86, v78, v78
	v_fmac_f32_e32 v87, v80, v80
	v_add_f32_e32 v86, v86, v87
	v_mul_f32_e32 v87, v75, v75
	v_fmac_f32_e32 v87, v74, v74
	v_add_f32_e32 v86, v86, v87
	v_mul_f32_e32 v87, v77, v77
	v_fmac_f32_e32 v87, v76, v76
	v_cvt_pk_bf16_f32 v78, v78, v79
	v_cvt_pk_bf16_f32 v79, v80, v81
	v_cvt_pk_bf16_f32 v81, v76, v77
	v_mul_f32_e32 v76, v71, v71
	v_mul_f32_e32 v77, v73, v73
	v_fmac_f32_e32 v76, v70, v70
	v_fmac_f32_e32 v77, v72, v72
	v_add_f32_e32 v76, v76, v77
	v_mul_f32_e32 v77, v67, v67
	v_fmac_f32_e32 v77, v66, v66
	v_add_f32_e32 v76, v76, v77
	v_mul_f32_e32 v77, v69, v69
	v_fmac_f32_e32 v77, v68, v68
	v_add_f32_e32 v86, v87, v86
	v_add_f32_e32 v76, v77, v76
	v_add_f32_e32 v76, v86, v76
	v_or_b32_e32 v82, 48, v142
	v_mov_b32_e32 v83, v143
	v_readlane_b32 s2, v253, 59
	v_mov_b32_e32 v77, v76
	s_nop 1
	v_permlane16_swap_b32_e32 v77, v76
	v_lshlrev_b64 v[84:85], 11, v[82:83]
	v_readlane_b32 s3, v253, 60
	v_cvt_pk_bf16_f32 v80, v74, v75
	s_nop 0
	v_lshl_add_u64 v[74:75], s[2:3], 0, v[84:85]
	v_lshl_add_u64 v[74:75], s[18:19], 1, v[74:75]
	v_lshl_add_u64 v[74:75], v[74:75], 0, s[68:69]
	v_lshl_add_u64 v[84:85], v[74:75], 0, v[0:1]
	v_cvt_pk_bf16_f32 v74, v70, v71
	s_waitcnt lgkmcnt(0)
	v_add_f32_e32 v70, v76, v77
	v_mov_b32_e32 v71, v70
	s_nop 1
	v_permlane32_swap_b32_e32 v71, v70
	v_cvt_pk_bf16_f32 v75, v72, v73
	v_cvt_pk_bf16_f32 v76, v66, v67
	v_cvt_pk_bf16_f32 v77, v68, v69
	global_store_dwordx4 v[84:85], v[78:81], off
	global_store_dwordx4 v[84:85], v[74:77], off offset:256
	s_and_saveexec_b64 s[2:3], s[0:1]
	s_cbranch_execz .LBB0_860
	v_readlane_b32 s20, v253, 57
	v_lshlrev_b64 v[66:67], 6, v[82:83]
	v_readlane_b32 s21, v253, 58
	s_waitcnt lgkmcnt(0)
	v_add_f32_e32 v68, v70, v71
	v_lshl_add_u64 v[66:67], s[20:21], 0, v[66:67]
	v_lshl_add_u64 v[66:67], s[16:17], 2, v[66:67]
	s_lshl_b32 s20, s29, 2
	s_mov_b32 s21, s69
	v_lshl_add_u64 v[66:67], v[66:67], 0, s[20:21]
	global_store_dword v[66:67], v68, off
.LBB0_860:
	s_or_b64 exec, exec, s[2:3]
	v_mul_f32_e32 v70, v63, v63
	s_waitcnt lgkmcnt(0)
	v_mul_f32_e32 v71, v65, v65
	v_fmac_f32_e32 v70, v62, v62
	v_fmac_f32_e32 v71, v64, v64
	v_add_f32_e32 v70, v70, v71
	v_mul_f32_e32 v71, v59, v59
	v_fmac_f32_e32 v71, v58, v58
	v_add_f32_e32 v70, v70, v71
	v_mul_f32_e32 v71, v61, v61
	v_fmac_f32_e32 v71, v60, v60
	v_cvt_pk_bf16_f32 v62, v62, v63
	v_cvt_pk_bf16_f32 v63, v64, v65
	v_cvt_pk_bf16_f32 v65, v60, v61
	v_mul_f32_e32 v60, v55, v55
	v_mul_f32_e32 v61, v57, v57
	v_fmac_f32_e32 v60, v54, v54
	v_fmac_f32_e32 v61, v56, v56
	v_add_f32_e32 v60, v60, v61
	v_mul_f32_e32 v61, v51, v51
	v_fmac_f32_e32 v61, v50, v50
	v_add_f32_e32 v60, v60, v61
	v_mul_f32_e32 v61, v53, v53
	v_fmac_f32_e32 v61, v52, v52
	v_add_f32_e32 v70, v71, v70
	v_add_f32_e32 v60, v61, v60
	v_add_f32_e32 v60, v70, v60
	v_lshl_add_u64 v[66:67], v[142:143], 0, s[44:45]
	v_readlane_b32 s2, v253, 59
	v_mov_b32_e32 v61, v60
	s_nop 1
	v_permlane16_swap_b32_e32 v61, v60
	v_lshlrev_b64 v[68:69], 11, v[66:67]
	v_readlane_b32 s3, v253, 60
	v_cvt_pk_bf16_f32 v64, v58, v59
	s_nop 0
	v_lshl_add_u64 v[58:59], s[2:3], 0, v[68:69]
	v_lshl_add_u64 v[58:59], s[18:19], 1, v[58:59]
	v_lshl_add_u64 v[58:59], v[58:59], 0, s[68:69]
	v_lshl_add_u64 v[68:69], v[58:59], 0, v[0:1]
	v_cvt_pk_bf16_f32 v58, v54, v55
	s_waitcnt lgkmcnt(0)
	v_add_f32_e32 v54, v60, v61
	v_mov_b32_e32 v55, v54
	s_nop 1
	v_permlane32_swap_b32_e32 v55, v54
	v_cvt_pk_bf16_f32 v59, v56, v57
	v_cvt_pk_bf16_f32 v60, v50, v51
	v_cvt_pk_bf16_f32 v61, v52, v53
	global_store_dwordx4 v[68:69], v[62:65], off
	global_store_dwordx4 v[68:69], v[58:61], off offset:256
	s_and_saveexec_b64 s[2:3], s[0:1]
	s_cbranch_execz .LBB0_862
	v_readlane_b32 s20, v253, 57
	v_lshlrev_b64 v[50:51], 6, v[66:67]
	v_readlane_b32 s21, v253, 58
	s_waitcnt lgkmcnt(0)
	v_add_f32_e32 v52, v54, v55
	v_lshl_add_u64 v[50:51], s[20:21], 0, v[50:51]
	v_lshl_add_u64 v[50:51], s[16:17], 2, v[50:51]
	s_lshl_b32 s20, s29, 2
	s_mov_b32 s21, s69
	v_lshl_add_u64 v[50:51], v[50:51], 0, s[20:21]
	global_store_dword v[50:51], v52, off
.LBB0_862:
	s_or_b64 exec, exec, s[2:3]
	v_mul_f32_e32 v54, v47, v47
	s_waitcnt lgkmcnt(0)
	v_mul_f32_e32 v55, v49, v49
	v_fmac_f32_e32 v54, v46, v46
	v_fmac_f32_e32 v55, v48, v48
	v_add_f32_e32 v54, v54, v55
	v_mul_f32_e32 v55, v43, v43
	v_fmac_f32_e32 v55, v42, v42
	v_add_f32_e32 v54, v54, v55
	v_mul_f32_e32 v55, v45, v45
	v_fmac_f32_e32 v55, v44, v44
	v_cvt_pk_bf16_f32 v46, v46, v47
	v_cvt_pk_bf16_f32 v47, v48, v49
	v_cvt_pk_bf16_f32 v49, v44, v45
	v_mul_f32_e32 v44, v39, v39
	v_mul_f32_e32 v45, v41, v41
	v_fmac_f32_e32 v44, v38, v38
	v_fmac_f32_e32 v45, v40, v40
	v_add_f32_e32 v44, v44, v45
	v_mul_f32_e32 v45, v35, v35
	v_fmac_f32_e32 v45, v34, v34
	v_add_f32_e32 v44, v44, v45
	v_mul_f32_e32 v45, v37, v37
	v_fmac_f32_e32 v45, v36, v36
	v_add_f32_e32 v54, v55, v54
	v_add_f32_e32 v44, v45, v44
	s_mov_b64 s[2:3], 0x90
	v_add_f32_e32 v44, v54, v44
	v_lshl_add_u64 v[50:51], v[142:143], 0, s[2:3]
	v_readlane_b32 s2, v253, 59
	v_mov_b32_e32 v45, v44
	s_nop 1
	v_permlane16_swap_b32_e32 v45, v44
	v_lshlrev_b64 v[52:53], 11, v[50:51]
	v_readlane_b32 s3, v253, 60
	v_cvt_pk_bf16_f32 v48, v42, v43
	s_nop 0
	v_lshl_add_u64 v[42:43], s[2:3], 0, v[52:53]
	v_lshl_add_u64 v[42:43], s[18:19], 1, v[42:43]
	v_lshl_add_u64 v[42:43], v[42:43], 0, s[68:69]
	v_lshl_add_u64 v[52:53], v[42:43], 0, v[0:1]
	v_cvt_pk_bf16_f32 v42, v38, v39
	s_waitcnt lgkmcnt(0)
	v_add_f32_e32 v38, v44, v45
	v_mov_b32_e32 v39, v38
	s_nop 1
	v_permlane32_swap_b32_e32 v39, v38
	v_cvt_pk_bf16_f32 v43, v40, v41
	v_cvt_pk_bf16_f32 v44, v34, v35
	v_cvt_pk_bf16_f32 v45, v36, v37
	global_store_dwordx4 v[52:53], v[46:49], off
	global_store_dwordx4 v[52:53], v[42:45], off offset:256
	s_and_saveexec_b64 s[2:3], s[0:1]
	s_cbranch_execz .LBB0_864
	v_readlane_b32 s20, v253, 57
	v_lshlrev_b64 v[34:35], 6, v[50:51]
	v_readlane_b32 s21, v253, 58
	s_waitcnt lgkmcnt(0)
	v_add_f32_e32 v36, v38, v39
	v_lshl_add_u64 v[34:35], s[20:21], 0, v[34:35]
	v_lshl_add_u64 v[34:35], s[16:17], 2, v[34:35]
	s_lshl_b32 s20, s29, 2
	s_mov_b32 s21, s69
	v_lshl_add_u64 v[34:35], v[34:35], 0, s[20:21]
	global_store_dword v[34:35], v36, off
.LBB0_864:
	s_or_b64 exec, exec, s[2:3]
	v_mul_f32_e32 v38, v31, v31
	s_waitcnt lgkmcnt(0)
	v_mul_f32_e32 v39, v33, v33
	v_fmac_f32_e32 v38, v30, v30
	v_fmac_f32_e32 v39, v32, v32
	v_add_f32_e32 v38, v38, v39
	v_mul_f32_e32 v39, v27, v27
	v_fmac_f32_e32 v39, v26, v26
	v_add_f32_e32 v38, v38, v39
	v_mul_f32_e32 v39, v29, v29
	v_fmac_f32_e32 v39, v28, v28
	v_cvt_pk_bf16_f32 v30, v30, v31
	v_cvt_pk_bf16_f32 v31, v32, v33
	v_cvt_pk_bf16_f32 v33, v28, v29
	v_mul_f32_e32 v28, v23, v23
	v_mul_f32_e32 v29, v25, v25
	v_fmac_f32_e32 v28, v22, v22
	v_fmac_f32_e32 v29, v24, v24
	v_add_f32_e32 v28, v28, v29
	v_mul_f32_e32 v29, v19, v19
	v_fmac_f32_e32 v29, v18, v18
	v_add_f32_e32 v28, v28, v29
	v_mul_f32_e32 v29, v21, v21
	v_fmac_f32_e32 v29, v20, v20
	v_add_f32_e32 v38, v39, v38
	v_add_f32_e32 v28, v29, v28
	s_mov_b64 s[2:3], 0xa0
	v_add_f32_e32 v28, v38, v28
	v_lshl_add_u64 v[34:35], v[142:143], 0, s[2:3]
	v_readlane_b32 s2, v253, 59
	v_mov_b32_e32 v29, v28
	s_nop 1
	v_permlane16_swap_b32_e32 v29, v28
	v_lshlrev_b64 v[36:37], 11, v[34:35]
	v_readlane_b32 s3, v253, 60
	v_cvt_pk_bf16_f32 v32, v26, v27
	s_nop 0
	v_lshl_add_u64 v[26:27], s[2:3], 0, v[36:37]
	v_lshl_add_u64 v[26:27], s[18:19], 1, v[26:27]
	v_lshl_add_u64 v[26:27], v[26:27], 0, s[68:69]
	v_lshl_add_u64 v[36:37], v[26:27], 0, v[0:1]
	v_cvt_pk_bf16_f32 v26, v22, v23
	s_waitcnt lgkmcnt(0)
	v_add_f32_e32 v22, v28, v29
	v_mov_b32_e32 v23, v22
	s_nop 1
	v_permlane32_swap_b32_e32 v23, v22
	v_cvt_pk_bf16_f32 v27, v24, v25
	v_cvt_pk_bf16_f32 v28, v18, v19
	v_cvt_pk_bf16_f32 v29, v20, v21
	global_store_dwordx4 v[36:37], v[30:33], off
	global_store_dwordx4 v[36:37], v[26:29], off offset:256
	s_and_saveexec_b64 s[2:3], s[0:1]
	s_cbranch_execz .LBB0_866
	v_readlane_b32 s20, v253, 57
	v_lshlrev_b64 v[18:19], 6, v[34:35]
	v_readlane_b32 s21, v253, 58
	s_waitcnt lgkmcnt(0)
	v_add_f32_e32 v20, v22, v23
	v_lshl_add_u64 v[18:19], s[20:21], 0, v[18:19]
	v_lshl_add_u64 v[18:19], s[16:17], 2, v[18:19]
	s_lshl_b32 s20, s29, 2
	s_mov_b32 s21, s69
	v_lshl_add_u64 v[18:19], v[18:19], 0, s[20:21]
	global_store_dword v[18:19], v20, off
.LBB0_866:
	s_or_b64 exec, exec, s[2:3]
	v_mul_f32_e32 v22, v15, v15
	s_waitcnt lgkmcnt(0)
	v_mul_f32_e32 v23, v17, v17
	v_fmac_f32_e32 v22, v14, v14
	v_fmac_f32_e32 v23, v16, v16
	v_add_f32_e32 v22, v22, v23
	v_mul_f32_e32 v23, v11, v11
	v_fmac_f32_e32 v23, v10, v10
	v_add_f32_e32 v22, v22, v23
	v_mul_f32_e32 v23, v13, v13
	v_fmac_f32_e32 v23, v12, v12
	v_cvt_pk_bf16_f32 v14, v14, v15
	v_cvt_pk_bf16_f32 v15, v16, v17
	v_cvt_pk_bf16_f32 v17, v12, v13
	v_mul_f32_e32 v12, v7, v7
	v_mul_f32_e32 v13, v9, v9
	v_fmac_f32_e32 v12, v6, v6
	v_fmac_f32_e32 v13, v8, v8
	v_add_f32_e32 v12, v12, v13
	v_mul_f32_e32 v13, v3, v3
	v_fmac_f32_e32 v13, v2, v2
	v_add_f32_e32 v12, v12, v13
	v_mul_f32_e32 v13, v5, v5
	v_fmac_f32_e32 v13, v4, v4
	v_add_f32_e32 v22, v23, v22
	v_add_f32_e32 v12, v13, v12
	s_mov_b64 s[2:3], 0xb0
	v_add_f32_e32 v12, v22, v12
	v_lshl_add_u64 v[18:19], v[142:143], 0, s[2:3]
	v_readlane_b32 s2, v253, 59
	v_mov_b32_e32 v13, v12
	s_nop 1
	v_permlane16_swap_b32_e32 v13, v12
	v_lshlrev_b64 v[20:21], 11, v[18:19]
	v_readlane_b32 s3, v253, 60
	v_cvt_pk_bf16_f32 v16, v10, v11
	s_nop 0
	v_lshl_add_u64 v[10:11], s[2:3], 0, v[20:21]
	v_lshl_add_u64 v[10:11], s[18:19], 1, v[10:11]
	v_lshl_add_u64 v[10:11], v[10:11], 0, s[68:69]
	v_lshl_add_u64 v[20:21], v[10:11], 0, v[0:1]
	s_waitcnt lgkmcnt(0)
	v_add_f32_e32 v0, v12, v13
	v_cvt_pk_bf16_f32 v10, v6, v7
	v_mov_b32_e32 v6, v0
	s_nop 1
	v_permlane32_swap_b32_e32 v6, v0
	v_cvt_pk_bf16_f32 v11, v8, v9
	v_cvt_pk_bf16_f32 v12, v2, v3
	v_cvt_pk_bf16_f32 v13, v4, v5
	global_store_dwordx4 v[20:21], v[14:17], off
	global_store_dwordx4 v[20:21], v[10:13], off offset:256
	s_and_saveexec_b64 s[2:3], s[0:1]
	s_cbranch_execz .LBB0_868
	v_readlane_b32 s18, v253, 57
	v_lshlrev_b64 v[2:3], 6, v[18:19]
	v_readlane_b32 s19, v253, 58
	s_lshl_b32 s68, s29, 2
	s_waitcnt lgkmcnt(0)
	v_add_f32_e32 v0, v0, v6
	v_lshl_add_u64 v[2:3], s[18:19], 0, v[2:3]
	v_lshl_add_u64 v[2:3], s[16:17], 2, v[2:3]
	v_lshl_add_u64 v[2:3], v[2:3], 0, s[68:69]
	global_store_dword v[2:3], v0, off
